# MLA: waves 4-7 also issue their tile writes in front of the PV MFMA they meet the barrier behind
# speedup vs baseline: 1.0225x; 1.0091x over previous
; __device__ __forceinline__ void finishSM9(f32x16& p0, f32x16& p1, float alpha, float& l_reg, v8i32& p8) {
; #pragma unroll
;   for (int r = 0; r < 16; ++r) { p0[r] = __builtin_amdgcn_exp2f(p0[r]); p1[r] = __builtin_amdgcn_exp2f(p1[r]); }
;   float ps = 0;
; #pragma unroll
;   for (int r = 0; r < 16; ++r) ps += p0[r];
; #pragma unroll
;   for (int r = 0; r < 16; ++r) ps += p1[r];
;   { auto rr = __builtin_amdgcn_permlane32_swap(__float_as_uint(ps), __float_as_uint(ps), false, false);
;     ps = __uint_as_float(rr[0]) + __uint_as_float(rr[1]); }
;   l_reg = l_reg * alpha + ps;
; #pragma unroll
;   for (int g = 0; g < 4; ++g) {
;     int w = __builtin_amdgcn_cvt_pk_fp8_f32(p0[4 * g], p0[4 * g + 1], 0, false); p8[g] = __builtin_amdgcn_cvt_pk_fp8_f32(p0[4 * g + 2], p0[4 * g + 3], w, true);
;     int u = __builtin_amdgcn_cvt_pk_fp8_f32(p1[4 * g], p1[4 * g + 1], 0, false); p8[4 + g] = __builtin_amdgcn_cvt_pk_fp8_f32(p1[4 * g + 2], p1[4 * g + 3], u, true); }
; }
; __device__ __forceinline__ void pv8(f32x16* o, const char* Vt, const v8i32 p8, int r32, int hi) {
;   const int sw = (r32 >> 2) & 3, a0 = r32 * 64 + (((hi * 2) ^ sw) << 4), a1 = r32 * 64 + (((hi * 2 + 1) ^ sw) << 4);
; #pragma unroll
;   for (int d0 = 0; d0 < 4; ++d0) {
;     const v8i32 vf = cat8(*reinterpret_cast<const v4i32*>(Vt + d0 * 2048 + a0), *reinterpret_cast<const v4i32*>(Vt + d0 * 2048 + a1));
;     o[d0] = __builtin_amdgcn_mfma_scale_f32_32x32x64_f8f6f4(p8, vf, o[d0], 0, 0, 0, 127, 0, 127); }
; }
; __device__ __forceinline__ void qkt9(f32x16& p0, f32x16& p1, const char* Kn, const char* Kr, const v8i32* qf, const float init, int r32, int hi) {
; #pragma unroll
;   for (int r = 0; r < 16; ++r) { p0[r] = init; p1[r] = init; }
; #pragma unroll
;   for (int s = 0; s < 2; ++s) { const int c0 = s * 4 + hi * 2;
;     const v8i32 a0 = cat8(*reinterpret_cast<const v4i32*>(Kn + KN8SW(r32, c0)), *reinterpret_cast<const v4i32*>(Kn + KN8SW(r32, c0 + 1)));
;     const v8i32 a1 = cat8(*reinterpret_cast<const v4i32*>(Kn + 4096 + KN8SW(r32, c0)), *reinterpret_cast<const v4i32*>(Kn + 4096 + KN8SW(r32, c0 + 1)));
;     p0 = __builtin_amdgcn_mfma_scale_f32_32x32x64_f8f6f4(a0, qf[s], p0, 0, 0, 0, 127, 0, 124);
;     p1 = __builtin_amdgcn_mfma_scale_f32_32x32x64_f8f6f4(a1, qf[s], p1, 0, 0, 0, 127, 0, 124); }
;   { const int c0 = hi * 2;
.Lmla_stag_loop:
	ds_read_b128 v[114:117], v215 offset:24576
	ds_read_b128 v[118:121], v216 offset:24576
	ds_read_b128 v[222:225], v215 offset:28672
	ds_read_b128 v[226:229], v216 offset:28672
	v_exp_f32_e32 v0, v82
	v_exp_f32_e32 v177, v83
	v_exp_f32_e32 v179, v84
	v_exp_f32_e32 v254, v85
	v_add_f32_e32 v219, v0, v177
	v_cvt_pk_fp8_f32 v246, v0, v177
	v_add_f32_e32 v219, v179, v219
	v_add_f32_e32 v219, v254, v219
	v_cvt_pk_fp8_f32 v246, v179, v254 op_sel:[0,0,1]
	s_waitcnt lgkmcnt(2)
	v_mfma_scale_f32_32x32x64_f8f6f4 v[114:129], v[114:121], v[146:153], v[230:245], v194, v193 op_sel_hi:[0,0,0]
	v_exp_f32_e32 v0, v86
	v_exp_f32_e32 v177, v87
	v_exp_f32_e32 v179, v88
	v_exp_f32_e32 v254, v89
	v_add_f32_e32 v219, v0, v219
	v_add_f32_e32 v219, v177, v219
	v_cvt_pk_fp8_f32 v247, v0, v177
	v_add_f32_e32 v219, v179, v219
	v_add_f32_e32 v219, v254, v219
	v_cvt_pk_fp8_f32 v247, v179, v254 op_sel:[0,0,1]
	ds_read_b128 v[82:85], v213 offset:24576
	ds_read_b128 v[86:89], v214 offset:24576
	s_waitcnt lgkmcnt(2)
	v_mfma_scale_f32_32x32x64_f8f6f4 v[98:113], v[222:229], v[146:153], v[230:245], v194, v193 op_sel_hi:[0,0,0]
	ds_read_b128 v[222:225], v213 offset:28672
	ds_read_b128 v[226:229], v214 offset:28672
	v_exp_f32_e32 v0, v90
	v_exp_f32_e32 v177, v91
	v_exp_f32_e32 v179, v92
	v_exp_f32_e32 v254, v93
	v_add_f32_e32 v219, v0, v219
	v_add_f32_e32 v219, v177, v219
	v_cvt_pk_fp8_f32 v248, v0, v177
	v_add_f32_e32 v219, v179, v219
	v_add_f32_e32 v219, v254, v219
	v_cvt_pk_fp8_f32 v248, v179, v254 op_sel:[0,0,1]
	v_exp_f32_e32 v0, v94
	v_exp_f32_e32 v177, v95
	v_exp_f32_e32 v179, v96
	v_exp_f32_e32 v254, v97
	v_add_f32_e32 v219, v0, v219
	v_add_f32_e32 v219, v177, v219
	v_cvt_pk_fp8_f32 v249, v0, v177
	v_add_f32_e32 v219, v179, v219
	v_add_f32_e32 v219, v254, v219
	v_cvt_pk_fp8_f32 v249, v179, v254 op_sel:[0,0,1]
	ds_read_b128 v[90:93], v185 offset:36864
	ds_read_b128 v[94:97], v186 offset:36864
	s_waitcnt lgkmcnt(4)
	v_mfma_scale_f32_32x32x64_f8f6f4 v[114:129], v[82:89], v[138:145], v[114:129], v194, v193 op_sel_hi:[0,0,0]
	v_exp_f32_e32 v0, v66
	v_exp_f32_e32 v177, v67
	v_exp_f32_e32 v179, v68
	v_exp_f32_e32 v254, v69
	v_add_f32_e32 v219, v0, v219
	v_add_f32_e32 v219, v177, v219
	v_cvt_pk_fp8_f32 v250, v0, v177
	v_add_f32_e32 v219, v179, v219
	v_add_f32_e32 v219, v254, v219
	v_cvt_pk_fp8_f32 v250, v179, v254 op_sel:[0,0,1]
	s_waitcnt lgkmcnt(2)
	v_mfma_scale_f32_32x32x64_f8f6f4 v[98:113], v[222:229], v[138:145], v[98:113], v194, v193 op_sel_hi:[0,0,0]
	ds_read_b128 v[222:225], v185 offset:38912
	ds_read_b128 v[226:229], v186 offset:38912
	v_exp_f32_e32 v0, v70
	v_exp_f32_e32 v177, v71
	v_exp_f32_e32 v179, v72
	v_exp_f32_e32 v254, v73
	v_add_f32_e32 v219, v0, v219
	v_add_f32_e32 v219, v177, v219
	v_cvt_pk_fp8_f32 v251, v0, v177
	v_add_f32_e32 v219, v179, v219
	v_add_f32_e32 v219, v254, v219
	v_cvt_pk_fp8_f32 v251, v179, v254 op_sel:[0,0,1]
	v_exp_f32_e32 v0, v74
	v_exp_f32_e32 v177, v75
	v_exp_f32_e32 v179, v76
	v_exp_f32_e32 v254, v77
	v_add_f32_e32 v219, v0, v219
	v_add_f32_e32 v219, v177, v219
	v_cvt_pk_fp8_f32 v252, v0, v177
	v_add_f32_e32 v219, v179, v219
	v_add_f32_e32 v219, v254, v219
	v_cvt_pk_fp8_f32 v252, v179, v254 op_sel:[0,0,1]
	s_waitcnt lgkmcnt(2)
	v_mfma_scale_f32_32x32x64_f8f6f4 v[114:129], v[90:97], v[130:137], v[114:129], v194, v193 op_sel_hi:[0,0,0]
	v_exp_f32_e32 v0, v78
	v_exp_f32_e32 v177, v79
	v_exp_f32_e32 v179, v80
	v_exp_f32_e32 v254, v81
	v_add_f32_e32 v219, v0, v219
	v_add_f32_e32 v219, v177, v219
	v_cvt_pk_fp8_f32 v253, v0, v177
	v_add_f32_e32 v219, v179, v219
	v_add_f32_e32 v219, v254, v219
	v_cvt_pk_fp8_f32 v253, v179, v254 op_sel:[0,0,1]
	ds_read_b128 v[90:93], v185 offset:0
	ds_read_b128 v[94:97], v186 offset:0
	ds_read_b128 v[82:85], v185 offset:2048
	ds_read_b128 v[86:89], v186 offset:2048
	ds_read_b128 v[74:77], v185 offset:4096
	ds_read_b128 v[78:81], v186 offset:4096
	ds_read_b128 v[66:69], v185 offset:6144
	ds_read_b128 v[70:73], v186 offset:6144
	s_waitcnt lgkmcnt(8)
	v_mfma_scale_f32_32x32x64_f8f6f4 v[98:113], v[222:229], v[130:137], v[98:113], v194, v193 op_sel_hi:[0,0,0]
	v_mov_b32_e32 v0, v219
	s_nop 1
	v_permlane32_swap_b32_e32 v219, v0
	v_add_f32_e32 v219, v219, v0
	v_fma_f32 v209, v209, v218, v219
	v_max_f32_e32 v177, v114, v115
	v_max3_f32 v177, v177, v116, v117
	v_max3_f32 v177, v177, v118, v119
	v_max3_f32 v177, v177, v120, v121
	v_max3_f32 v177, v177, v122, v123
	v_max3_f32 v177, v177, v124, v125
	v_max3_f32 v177, v177, v126, v127
	v_max3_f32 v177, v177, v128, v129
	s_waitcnt lgkmcnt(6)
	v_mfma_scale_f32_32x32x64_f8f6f4 v[50:65], v[246:253], v[90:97], v[50:65], v194, v194 op_sel_hi:[0,0,0]
	s_waitcnt vmcnt(0)
	ds_write_b128 v210, v[158:161] offset:43008
	ds_write_b128 v211, v[162:165] offset:51200
	s_waitcnt lgkmcnt(6)
	v_mfma_scale_f32_32x32x64_f8f6f4 v[34:49], v[246:253], v[82:89], v[34:49], v194, v194 op_sel_hi:[0,0,0]
	s_waitcnt lgkmcnt(0)
	s_barrier
	global_load_dwordx4 v[158:161], v176, s[18:19]
	global_load_dwordx4 v[162:165], v178, s[16:17]
	v_add_u32_e32 v176, 0x2000, v176
	v_add_u32_e32 v178, 0x20000, v178
	s_waitcnt lgkmcnt(2)
	v_mfma_scale_f32_32x32x64_f8f6f4 v[18:33], v[246:253], v[74:81], v[18:33], v194, v194 op_sel_hi:[0,0,0]
	s_waitcnt lgkmcnt(0)
	v_mfma_scale_f32_32x32x64_f8f6f4 v[2:17], v[246:253], v[66:73], v[2:17], v194, v194 op_sel_hi:[0,0,0]
	v_max_f32_e32 v0, v98, v99
	v_max3_f32 v0, v0, v100, v101
	v_max3_f32 v0, v0, v102, v103
	v_max3_f32 v0, v0, v104, v105
	v_max3_f32 v0, v0, v106, v107
	v_max3_f32 v0, v0, v108, v109
	v_max3_f32 v0, v0, v110, v111
	v_max3_f32 v0, v0, v112, v113
	v_max_f32_e32 v177, v177, v0
	v_mov_b32_e32 v0, v177
	v_mov_b32_e32 v221, 1.0
	s_nop 0
	v_permlane32_swap_b32_e32 v177, v0
	v_max_f32_e32 v177, v177, v0
	v_cmp_ge_f32_e32 vcc, s90, v177
	s_cmp_eq_u64 vcc, exec
	s_cbranch_scc0 .Lmla_s0_newmax
; __device__ __forceinline__ void finishSM9(f32x16& p0, f32x16& p1, float alpha, float& l_reg, v8i32& p8) {
; #pragma unroll
;   for (int r = 0; r < 16; ++r) { p0[r] = __builtin_amdgcn_exp2f(p0[r]); p1[r] = __builtin_amdgcn_exp2f(p1[r]); }
;   float ps = 0;
; #pragma unroll
;   for (int r = 0; r < 16; ++r) ps += p0[r];
; #pragma unroll
;   for (int r = 0; r < 16; ++r) ps += p1[r];
;   { auto rr = __builtin_amdgcn_permlane32_swap(__float_as_uint(ps), __float_as_uint(ps), false, false);
;     ps = __uint_as_float(rr[0]) + __uint_as_float(rr[1]); }
;   l_reg = l_reg * alpha + ps;
; #pragma unroll
;   for (int g = 0; g < 4; ++g) {
;     int w = __builtin_amdgcn_cvt_pk_fp8_f32(p0[4 * g], p0[4 * g + 1], 0, false); p8[g] = __builtin_amdgcn_cvt_pk_fp8_f32(p0[4 * g + 2], p0[4 * g + 3], w, true);
;     int u = __builtin_amdgcn_cvt_pk_fp8_f32(p1[4 * g], p1[4 * g + 1], 0, false); p8[4 + g] = __builtin_amdgcn_cvt_pk_fp8_f32(p1[4 * g + 2], p1[4 * g + 3], u, true); }
; }
; __device__ __forceinline__ void pv8(f32x16* o, const char* Vt, const v8i32 p8, int r32, int hi) {
;   const int sw = (r32 >> 2) & 3, a0 = r32 * 64 + (((hi * 2) ^ sw) << 4), a1 = r32 * 64 + (((hi * 2 + 1) ^ sw) << 4);
; #pragma unroll
;   for (int d0 = 0; d0 < 4; ++d0) {
;     const v8i32 vf = cat8(*reinterpret_cast<const v4i32*>(Vt + d0 * 2048 + a0), *reinterpret_cast<const v4i32*>(Vt + d0 * 2048 + a1));
;     o[d0] = __builtin_amdgcn_mfma_scale_f32_32x32x64_f8f6f4(p8, vf, o[d0], 0, 0, 0, 127, 0, 127); }
; }
; __device__ __forceinline__ void qkt9(f32x16& p0, f32x16& p1, const char* Kn, const char* Kr, const v8i32* qf, const float init, int r32, int hi) {
; #pragma unroll
;   for (int r = 0; r < 16; ++r) { p0[r] = init; p1[r] = init; }
; #pragma unroll
;   for (int s = 0; s < 2; ++s) { const int c0 = s * 4 + hi * 2;
;     const v8i32 a0 = cat8(*reinterpret_cast<const v4i32*>(Kn + KN8SW(r32, c0)), *reinterpret_cast<const v4i32*>(Kn + KN8SW(r32, c0 + 1)));
;     const v8i32 a1 = cat8(*reinterpret_cast<const v4i32*>(Kn + 4096 + KN8SW(r32, c0)), *reinterpret_cast<const v4i32*>(Kn + 4096 + KN8SW(r32, c0 + 1)));
;     p0 = __builtin_amdgcn_mfma_scale_f32_32x32x64_f8f6f4(a0, qf[s], p0, 0, 0, 0, 127, 0, 124);
;     p1 = __builtin_amdgcn_mfma_scale_f32_32x32x64_f8f6f4(a1, qf[s], p1, 0, 0, 0, 127, 0, 124); }
;   { const int c0 = hi * 2;
.Lmla_s0_cont:
	ds_read_b128 v[82:85], v215 offset:51200
	ds_read_b128 v[86:89], v216 offset:51200
	ds_read_b128 v[222:225], v215 offset:55296
	ds_read_b128 v[226:229], v216 offset:55296
	v_exp_f32_e32 v0, v114
	v_exp_f32_e32 v177, v115
	v_exp_f32_e32 v179, v116
	v_exp_f32_e32 v254, v117
	v_add_f32_e32 v219, v0, v177
	v_cvt_pk_fp8_f32 v246, v0, v177
	v_add_f32_e32 v219, v179, v219
	v_add_f32_e32 v219, v254, v219
	v_cvt_pk_fp8_f32 v246, v179, v254 op_sel:[0,0,1]
	s_waitcnt lgkmcnt(2)
	v_mfma_scale_f32_32x32x64_f8f6f4 v[82:97], v[82:89], v[146:153], v[230:245], v194, v193 op_sel_hi:[0,0,0]
	v_exp_f32_e32 v0, v118
	v_exp_f32_e32 v177, v119
	v_exp_f32_e32 v179, v120
	v_exp_f32_e32 v254, v121
	v_add_f32_e32 v219, v0, v219
	v_add_f32_e32 v219, v177, v219
	v_cvt_pk_fp8_f32 v247, v0, v177
	v_add_f32_e32 v219, v179, v219
	v_add_f32_e32 v219, v254, v219
	v_cvt_pk_fp8_f32 v247, v179, v254 op_sel:[0,0,1]
	ds_read_b128 v[114:117], v213 offset:51200
	ds_read_b128 v[118:121], v214 offset:51200
	s_waitcnt lgkmcnt(2)
	v_mfma_scale_f32_32x32x64_f8f6f4 v[66:81], v[222:229], v[146:153], v[230:245], v194, v193 op_sel_hi:[0,0,0]
	ds_read_b128 v[222:225], v213 offset:55296
	ds_read_b128 v[226:229], v214 offset:55296
	v_exp_f32_e32 v0, v122
	v_exp_f32_e32 v177, v123
	v_exp_f32_e32 v179, v124
	v_exp_f32_e32 v254, v125
	v_add_f32_e32 v219, v0, v219
	v_add_f32_e32 v219, v177, v219
	v_cvt_pk_fp8_f32 v248, v0, v177
	v_add_f32_e32 v219, v179, v219
	v_add_f32_e32 v219, v254, v219
	v_cvt_pk_fp8_f32 v248, v179, v254 op_sel:[0,0,1]
	v_exp_f32_e32 v0, v126
	v_exp_f32_e32 v177, v127
	v_exp_f32_e32 v179, v128
	v_exp_f32_e32 v254, v129
	v_add_f32_e32 v219, v0, v219
	v_add_f32_e32 v219, v177, v219
	v_cvt_pk_fp8_f32 v249, v0, v177
	v_add_f32_e32 v219, v179, v219
	v_add_f32_e32 v219, v254, v219
	v_cvt_pk_fp8_f32 v249, v179, v254 op_sel:[0,0,1]
	ds_read_b128 v[122:125], v185 offset:59392
	ds_read_b128 v[126:129], v186 offset:59392
	s_waitcnt lgkmcnt(4)
	v_mfma_scale_f32_32x32x64_f8f6f4 v[82:97], v[114:121], v[138:145], v[82:97], v194, v193 op_sel_hi:[0,0,0]
	v_exp_f32_e32 v0, v98
	v_exp_f32_e32 v177, v99
	v_exp_f32_e32 v179, v100
	v_exp_f32_e32 v254, v101
	v_add_f32_e32 v219, v0, v219
	v_add_f32_e32 v219, v177, v219
	v_cvt_pk_fp8_f32 v250, v0, v177
	v_add_f32_e32 v219, v179, v219
	v_add_f32_e32 v219, v254, v219
	v_cvt_pk_fp8_f32 v250, v179, v254 op_sel:[0,0,1]
	s_waitcnt lgkmcnt(2)
	v_mfma_scale_f32_32x32x64_f8f6f4 v[66:81], v[222:229], v[138:145], v[66:81], v194, v193 op_sel_hi:[0,0,0]
	ds_read_b128 v[222:225], v185 offset:61440
	ds_read_b128 v[226:229], v186 offset:61440
	v_exp_f32_e32 v0, v102
	v_exp_f32_e32 v177, v103
	v_exp_f32_e32 v179, v104
	v_exp_f32_e32 v254, v105
	v_add_f32_e32 v219, v0, v219
	v_add_f32_e32 v219, v177, v219
	v_cvt_pk_fp8_f32 v251, v0, v177
	v_add_f32_e32 v219, v179, v219
	v_add_f32_e32 v219, v254, v219
	v_cvt_pk_fp8_f32 v251, v179, v254 op_sel:[0,0,1]
	v_exp_f32_e32 v0, v106
	v_exp_f32_e32 v177, v107
	v_exp_f32_e32 v179, v108
	v_exp_f32_e32 v254, v109
	v_add_f32_e32 v219, v0, v219
	v_add_f32_e32 v219, v177, v219
	v_cvt_pk_fp8_f32 v252, v0, v177
	v_add_f32_e32 v219, v179, v219
	v_add_f32_e32 v219, v254, v219
	v_cvt_pk_fp8_f32 v252, v179, v254 op_sel:[0,0,1]
	s_waitcnt lgkmcnt(2)
	v_mfma_scale_f32_32x32x64_f8f6f4 v[82:97], v[122:129], v[130:137], v[82:97], v194, v193 op_sel_hi:[0,0,0]
	v_exp_f32_e32 v0, v110
	v_exp_f32_e32 v177, v111
	v_exp_f32_e32 v179, v112
	v_exp_f32_e32 v254, v113
	v_add_f32_e32 v219, v0, v219
	v_add_f32_e32 v219, v177, v219
	v_cvt_pk_fp8_f32 v253, v0, v177
	v_add_f32_e32 v219, v179, v219
	v_add_f32_e32 v219, v254, v219
	v_cvt_pk_fp8_f32 v253, v179, v254 op_sel:[0,0,1]
	ds_read_b128 v[122:125], v185 offset:8192
	ds_read_b128 v[126:129], v186 offset:8192
	ds_read_b128 v[114:117], v185 offset:10240
	ds_read_b128 v[118:121], v186 offset:10240
	ds_read_b128 v[106:109], v185 offset:12288
	ds_read_b128 v[110:113], v186 offset:12288
	ds_read_b128 v[98:101], v185 offset:14336
	ds_read_b128 v[102:105], v186 offset:14336
	s_waitcnt lgkmcnt(8)
	v_mfma_scale_f32_32x32x64_f8f6f4 v[66:81], v[222:229], v[130:137], v[66:81], v194, v193 op_sel_hi:[0,0,0]
	v_mov_b32_e32 v0, v219
	s_nop 1
	v_permlane32_swap_b32_e32 v219, v0
	v_add_f32_e32 v219, v219, v0
	v_fma_f32 v209, v209, v221, v219
	v_max_f32_e32 v177, v82, v83
	v_max3_f32 v177, v177, v84, v85
	v_max3_f32 v177, v177, v86, v87
	v_max3_f32 v177, v177, v88, v89
	v_max3_f32 v177, v177, v90, v91
	v_max3_f32 v177, v177, v92, v93
	v_max3_f32 v177, v177, v94, v95
	v_max3_f32 v177, v177, v96, v97
	s_waitcnt lgkmcnt(6)
	v_mfma_scale_f32_32x32x64_f8f6f4 v[50:65], v[246:253], v[122:129], v[50:65], v194, v194 op_sel_hi:[0,0,0]
	s_waitcnt vmcnt(0)
	ds_write_b128 v210, v[158:161]
	ds_write_b128 v211, v[162:165] offset:16384
	s_waitcnt lgkmcnt(6)
	v_mfma_scale_f32_32x32x64_f8f6f4 v[34:49], v[246:253], v[114:121], v[34:49], v194, v194 op_sel_hi:[0,0,0]
	s_waitcnt lgkmcnt(0)
	s_barrier
	global_load_dwordx4 v[158:161], v176, s[18:19]
	global_load_dwordx4 v[162:165], v178, s[16:17]
	v_add_u32_e32 v176, 0x2000, v176
	v_add_u32_e32 v178, 0x20000, v178
	s_waitcnt lgkmcnt(2)
	v_mfma_scale_f32_32x32x64_f8f6f4 v[18:33], v[246:253], v[106:113], v[18:33], v194, v194 op_sel_hi:[0,0,0]
	s_waitcnt lgkmcnt(0)
	v_mfma_scale_f32_32x32x64_f8f6f4 v[2:17], v[246:253], v[98:105], v[2:17], v194, v194 op_sel_hi:[0,0,0]
	v_max_f32_e32 v0, v66, v67
	v_max3_f32 v0, v0, v68, v69
	v_max3_f32 v0, v0, v70, v71
	v_max3_f32 v0, v0, v72, v73
	v_max3_f32 v0, v0, v74, v75
	v_max3_f32 v0, v0, v76, v77
	v_max3_f32 v0, v0, v78, v79
	v_max3_f32 v0, v0, v80, v81
	v_max_f32_e32 v177, v177, v0
	v_mov_b32_e32 v0, v177
	v_mov_b32_e32 v218, 1.0
	s_nop 0
	v_permlane32_swap_b32_e32 v177, v0
	v_max_f32_e32 v177, v177, v0
	v_cmp_ge_f32_e32 vcc, s90, v177
	s_cmp_eq_u64 vcc, exec
	s_cbranch_scc0 .Lmla_s1_newmax
; __device__ __forceinline__ void finishSM9(f32x16& p0, f32x16& p1, float alpha, float& l_reg, v8i32& p8) {
; #pragma unroll
;   for (int r = 0; r < 16; ++r) { p0[r] = __builtin_amdgcn_exp2f(p0[r]); p1[r] = __builtin_amdgcn_exp2f(p1[r]); }
;   float ps = 0;
; #pragma unroll
;   for (int r = 0; r < 16; ++r) ps += p0[r];
; #pragma unroll
;   for (int r = 0; r < 16; ++r) ps += p1[r];
;   { auto rr = __builtin_amdgcn_permlane32_swap(__float_as_uint(ps), __float_as_uint(ps), false, false);
;     ps = __uint_as_float(rr[0]) + __uint_as_float(rr[1]); }
;   l_reg = l_reg * alpha + ps;
; #pragma unroll
;   for (int g = 0; g < 4; ++g) {
;     int w = __builtin_amdgcn_cvt_pk_fp8_f32(p0[4 * g], p0[4 * g + 1], 0, false); p8[g] = __builtin_amdgcn_cvt_pk_fp8_f32(p0[4 * g + 2], p0[4 * g + 3], w, true);
;     int u = __builtin_amdgcn_cvt_pk_fp8_f32(p1[4 * g], p1[4 * g + 1], 0, false); p8[4 + g] = __builtin_amdgcn_cvt_pk_fp8_f32(p1[4 * g + 2], p1[4 * g + 3], u, true); }
; }
; __device__ __forceinline__ void pv8(f32x16* o, const char* Vt, const v8i32 p8, int r32, int hi) {
;   const int sw = (r32 >> 2) & 3, a0 = r32 * 64 + (((hi * 2) ^ sw) << 4), a1 = r32 * 64 + (((hi * 2 + 1) ^ sw) << 4);
; #pragma unroll
;   for (int d0 = 0; d0 < 4; ++d0) {
;     const v8i32 vf = cat8(*reinterpret_cast<const v4i32*>(Vt + d0 * 2048 + a0), *reinterpret_cast<const v4i32*>(Vt + d0 * 2048 + a1));
;     o[d0] = __builtin_amdgcn_mfma_scale_f32_32x32x64_f8f6f4(p8, vf, o[d0], 0, 0, 0, 127, 0, 127); }
; }
; __device__ __forceinline__ void qkt9(f32x16& p0, f32x16& p1, const char* Kn, const char* Kr, const v8i32* qf, const float init, int r32, int hi) {
; #pragma unroll
;   for (int r = 0; r < 16; ++r) { p0[r] = init; p1[r] = init; }
; #pragma unroll
;   for (int s = 0; s < 2; ++s) { const int c0 = s * 4 + hi * 2;
;     const v8i32 a0 = cat8(*reinterpret_cast<const v4i32*>(Kn + KN8SW(r32, c0)), *reinterpret_cast<const v4i32*>(Kn + KN8SW(r32, c0 + 1)));
;     const v8i32 a1 = cat8(*reinterpret_cast<const v4i32*>(Kn + 4096 + KN8SW(r32, c0)), *reinterpret_cast<const v4i32*>(Kn + 4096 + KN8SW(r32, c0 + 1)));
;     p0 = __builtin_amdgcn_mfma_scale_f32_32x32x64_f8f6f4(a0, qf[s], p0, 0, 0, 0, 127, 0, 124);
;     p1 = __builtin_amdgcn_mfma_scale_f32_32x32x64_f8f6f4(a1, qf[s], p1, 0, 0, 0, 127, 0, 124); }
;   { const int c0 = hi * 2;
.Lmla_s1_cont:
	ds_read_b128 v[114:117], v215 offset:16384
	ds_read_b128 v[118:121], v216 offset:16384
	ds_read_b128 v[222:225], v215 offset:20480
	ds_read_b128 v[226:229], v216 offset:20480
	v_exp_f32_e32 v0, v82
	v_exp_f32_e32 v177, v83
	v_exp_f32_e32 v179, v84
	v_exp_f32_e32 v254, v85
	v_add_f32_e32 v219, v0, v177
	v_cvt_pk_fp8_f32 v246, v0, v177
	v_add_f32_e32 v219, v179, v219
	v_add_f32_e32 v219, v254, v219
	v_cvt_pk_fp8_f32 v246, v179, v254 op_sel:[0,0,1]
	s_waitcnt lgkmcnt(2)
	v_mfma_scale_f32_32x32x64_f8f6f4 v[114:129], v[114:121], v[146:153], v[230:245], v194, v193 op_sel_hi:[0,0,0]
	v_exp_f32_e32 v0, v86
	v_exp_f32_e32 v177, v87
	v_exp_f32_e32 v179, v88
	v_exp_f32_e32 v254, v89
	v_add_f32_e32 v219, v0, v219
	v_add_f32_e32 v219, v177, v219
	v_cvt_pk_fp8_f32 v247, v0, v177
	v_add_f32_e32 v219, v179, v219
	v_add_f32_e32 v219, v254, v219
	v_cvt_pk_fp8_f32 v247, v179, v254 op_sel:[0,0,1]
	ds_read_b128 v[82:85], v213 offset:16384
	ds_read_b128 v[86:89], v214 offset:16384
	s_waitcnt lgkmcnt(2)
	v_mfma_scale_f32_32x32x64_f8f6f4 v[98:113], v[222:229], v[146:153], v[230:245], v194, v193 op_sel_hi:[0,0,0]
	ds_read_b128 v[222:225], v213 offset:20480
	ds_read_b128 v[226:229], v214 offset:20480
	v_exp_f32_e32 v0, v90
	v_exp_f32_e32 v177, v91
	v_exp_f32_e32 v179, v92
	v_exp_f32_e32 v254, v93
	v_add_f32_e32 v219, v0, v219
	v_add_f32_e32 v219, v177, v219
	v_cvt_pk_fp8_f32 v248, v0, v177
	v_add_f32_e32 v219, v179, v219
	v_add_f32_e32 v219, v254, v219
	v_cvt_pk_fp8_f32 v248, v179, v254 op_sel:[0,0,1]
	v_exp_f32_e32 v0, v94
	v_exp_f32_e32 v177, v95
	v_exp_f32_e32 v179, v96
	v_exp_f32_e32 v254, v97
	v_add_f32_e32 v219, v0, v219
	v_add_f32_e32 v219, v177, v219
	v_cvt_pk_fp8_f32 v249, v0, v177
	v_add_f32_e32 v219, v179, v219
	v_add_f32_e32 v219, v254, v219
	v_cvt_pk_fp8_f32 v249, v179, v254 op_sel:[0,0,1]
	ds_read_b128 v[90:93], v185 offset:32768
	ds_read_b128 v[94:97], v186 offset:32768
	s_waitcnt lgkmcnt(4)
	v_mfma_scale_f32_32x32x64_f8f6f4 v[114:129], v[82:89], v[138:145], v[114:129], v194, v193 op_sel_hi:[0,0,0]
	v_exp_f32_e32 v0, v66
	v_exp_f32_e32 v177, v67
	v_exp_f32_e32 v179, v68
	v_exp_f32_e32 v254, v69
	v_add_f32_e32 v219, v0, v219
	v_add_f32_e32 v219, v177, v219
	v_cvt_pk_fp8_f32 v250, v0, v177
	v_add_f32_e32 v219, v179, v219
	v_add_f32_e32 v219, v254, v219
	v_cvt_pk_fp8_f32 v250, v179, v254 op_sel:[0,0,1]
	s_waitcnt lgkmcnt(2)
	v_mfma_scale_f32_32x32x64_f8f6f4 v[98:113], v[222:229], v[138:145], v[98:113], v194, v193 op_sel_hi:[0,0,0]
	ds_read_b128 v[222:225], v185 offset:34816
	ds_read_b128 v[226:229], v186 offset:34816
	v_exp_f32_e32 v0, v70
	v_exp_f32_e32 v177, v71
	v_exp_f32_e32 v179, v72
	v_exp_f32_e32 v254, v73
	v_add_f32_e32 v219, v0, v219
	v_add_f32_e32 v219, v177, v219
	v_cvt_pk_fp8_f32 v251, v0, v177
	v_add_f32_e32 v219, v179, v219
	v_add_f32_e32 v219, v254, v219
	v_cvt_pk_fp8_f32 v251, v179, v254 op_sel:[0,0,1]
	v_exp_f32_e32 v0, v74
	v_exp_f32_e32 v177, v75
	v_exp_f32_e32 v179, v76
	v_exp_f32_e32 v254, v77
	v_add_f32_e32 v219, v0, v219
	v_add_f32_e32 v219, v177, v219
	v_cvt_pk_fp8_f32 v252, v0, v177
	v_add_f32_e32 v219, v179, v219
	v_add_f32_e32 v219, v254, v219
	v_cvt_pk_fp8_f32 v252, v179, v254 op_sel:[0,0,1]
	s_waitcnt lgkmcnt(2)
	v_mfma_scale_f32_32x32x64_f8f6f4 v[114:129], v[90:97], v[130:137], v[114:129], v194, v193 op_sel_hi:[0,0,0]
	v_exp_f32_e32 v0, v78
	v_exp_f32_e32 v177, v79
	v_exp_f32_e32 v179, v80
	v_exp_f32_e32 v254, v81
	v_add_f32_e32 v219, v0, v219
	v_add_f32_e32 v219, v177, v219
	v_cvt_pk_fp8_f32 v253, v0, v177
	v_add_f32_e32 v219, v179, v219
	v_add_f32_e32 v219, v254, v219
	v_cvt_pk_fp8_f32 v253, v179, v254 op_sel:[0,0,1]
	ds_read_b128 v[90:93], v185 offset:43008
	ds_read_b128 v[94:97], v186 offset:43008
	ds_read_b128 v[82:85], v185 offset:45056
	ds_read_b128 v[86:89], v186 offset:45056
	ds_read_b128 v[74:77], v185 offset:47104
	ds_read_b128 v[78:81], v186 offset:47104
	ds_read_b128 v[66:69], v185 offset:49152
	ds_read_b128 v[70:73], v186 offset:49152
	s_waitcnt lgkmcnt(8)
	v_mfma_scale_f32_32x32x64_f8f6f4 v[98:113], v[222:229], v[130:137], v[98:113], v194, v193 op_sel_hi:[0,0,0]
	v_mov_b32_e32 v0, v219
	s_nop 1
	v_permlane32_swap_b32_e32 v219, v0
	v_add_f32_e32 v219, v219, v0
	v_fma_f32 v209, v209, v218, v219
	v_max_f32_e32 v177, v114, v115
	v_max3_f32 v177, v177, v116, v117
	v_max3_f32 v177, v177, v118, v119
	v_max3_f32 v177, v177, v120, v121
	v_max3_f32 v177, v177, v122, v123
	v_max3_f32 v177, v177, v124, v125
	v_max3_f32 v177, v177, v126, v127
	v_max3_f32 v177, v177, v128, v129
	s_waitcnt lgkmcnt(6)
	v_mfma_scale_f32_32x32x64_f8f6f4 v[50:65], v[246:253], v[90:97], v[50:65], v194, v194 op_sel_hi:[0,0,0]
	s_waitcnt vmcnt(0)
	ds_write_b128 v210, v[158:161] offset:8192
	ds_write_b128 v211, v[162:165] offset:24576
	s_waitcnt lgkmcnt(6)
	v_mfma_scale_f32_32x32x64_f8f6f4 v[34:49], v[246:253], v[82:89], v[34:49], v194, v194 op_sel_hi:[0,0,0]
	s_waitcnt lgkmcnt(0)
	s_barrier
	global_load_dwordx4 v[158:161], v176, s[18:19]
	global_load_dwordx4 v[162:165], v178, s[16:17]
	v_add_u32_e32 v176, 0x2000, v176
	v_add_u32_e32 v178, 0x20000, v178
	s_waitcnt lgkmcnt(2)
	v_mfma_scale_f32_32x32x64_f8f6f4 v[18:33], v[246:253], v[74:81], v[18:33], v194, v194 op_sel_hi:[0,0,0]
	s_waitcnt lgkmcnt(0)
	v_mfma_scale_f32_32x32x64_f8f6f4 v[2:17], v[246:253], v[66:73], v[2:17], v194, v194 op_sel_hi:[0,0,0]
	v_max_f32_e32 v0, v98, v99
	v_max3_f32 v0, v0, v100, v101
	v_max3_f32 v0, v0, v102, v103
	v_max3_f32 v0, v0, v104, v105
	v_max3_f32 v0, v0, v106, v107
	v_max3_f32 v0, v0, v108, v109
	v_max3_f32 v0, v0, v110, v111
	v_max3_f32 v0, v0, v112, v113
	v_max_f32_e32 v177, v177, v0
	v_mov_b32_e32 v0, v177
	v_mov_b32_e32 v221, 1.0
	s_nop 0
	v_permlane32_swap_b32_e32 v177, v0
	v_max_f32_e32 v177, v177, v0
	v_cmp_ge_f32_e32 vcc, s90, v177
	s_cmp_eq_u64 vcc, exec
	s_cbranch_scc0 .Lmla_s2_newmax
; __device__ __forceinline__ void finishSM9(f32x16& p0, f32x16& p1, float alpha, float& l_reg, v8i32& p8) {
; #pragma unroll
;   for (int r = 0; r < 16; ++r) { p0[r] = __builtin_amdgcn_exp2f(p0[r]); p1[r] = __builtin_amdgcn_exp2f(p1[r]); }
;   float ps = 0;
; #pragma unroll
;   for (int r = 0; r < 16; ++r) ps += p0[r];
; #pragma unroll
;   for (int r = 0; r < 16; ++r) ps += p1[r];
;   { auto rr = __builtin_amdgcn_permlane32_swap(__float_as_uint(ps), __float_as_uint(ps), false, false);
;     ps = __uint_as_float(rr[0]) + __uint_as_float(rr[1]); }
;   l_reg = l_reg * alpha + ps;
; #pragma unroll
;   for (int g = 0; g < 4; ++g) {
;     int w = __builtin_amdgcn_cvt_pk_fp8_f32(p0[4 * g], p0[4 * g + 1], 0, false); p8[g] = __builtin_amdgcn_cvt_pk_fp8_f32(p0[4 * g + 2], p0[4 * g + 3], w, true);
;     int u = __builtin_amdgcn_cvt_pk_fp8_f32(p1[4 * g], p1[4 * g + 1], 0, false); p8[4 + g] = __builtin_amdgcn_cvt_pk_fp8_f32(p1[4 * g + 2], p1[4 * g + 3], u, true); }
; }
; __device__ __forceinline__ void pv8(f32x16* o, const char* Vt, const v8i32 p8, int r32, int hi) {
;   const int sw = (r32 >> 2) & 3, a0 = r32 * 64 + (((hi * 2) ^ sw) << 4), a1 = r32 * 64 + (((hi * 2 + 1) ^ sw) << 4);
; #pragma unroll
;   for (int d0 = 0; d0 < 4; ++d0) {
;     const v8i32 vf = cat8(*reinterpret_cast<const v4i32*>(Vt + d0 * 2048 + a0), *reinterpret_cast<const v4i32*>(Vt + d0 * 2048 + a1));
;     o[d0] = __builtin_amdgcn_mfma_scale_f32_32x32x64_f8f6f4(p8, vf, o[d0], 0, 0, 0, 127, 0, 127); }
; }
; __device__ __forceinline__ void qkt9(f32x16& p0, f32x16& p1, const char* Kn, const char* Kr, const v8i32* qf, const float init, int r32, int hi) {
; #pragma unroll
;   for (int r = 0; r < 16; ++r) { p0[r] = init; p1[r] = init; }
; #pragma unroll
;   for (int s = 0; s < 2; ++s) { const int c0 = s * 4 + hi * 2;
;     const v8i32 a0 = cat8(*reinterpret_cast<const v4i32*>(Kn + KN8SW(r32, c0)), *reinterpret_cast<const v4i32*>(Kn + KN8SW(r32, c0 + 1)));
;     const v8i32 a1 = cat8(*reinterpret_cast<const v4i32*>(Kn + 4096 + KN8SW(r32, c0)), *reinterpret_cast<const v4i32*>(Kn + 4096 + KN8SW(r32, c0 + 1)));
;     p0 = __builtin_amdgcn_mfma_scale_f32_32x32x64_f8f6f4(a0, qf[s], p0, 0, 0, 0, 127, 0, 124);
;     p1 = __builtin_amdgcn_mfma_scale_f32_32x32x64_f8f6f4(a1, qf[s], p1, 0, 0, 0, 127, 0, 124); }
;   { const int c0 = hi * 2;
.Lmla_s2_cont:
	ds_read_b128 v[82:85], v215 offset:24576
	ds_read_b128 v[86:89], v216 offset:24576
	ds_read_b128 v[222:225], v215 offset:28672
	ds_read_b128 v[226:229], v216 offset:28672
	v_exp_f32_e32 v0, v114
	v_exp_f32_e32 v177, v115
	v_exp_f32_e32 v179, v116
	v_exp_f32_e32 v254, v117
	v_add_f32_e32 v219, v0, v177
	v_cvt_pk_fp8_f32 v246, v0, v177
	v_add_f32_e32 v219, v179, v219
	v_add_f32_e32 v219, v254, v219
	v_cvt_pk_fp8_f32 v246, v179, v254 op_sel:[0,0,1]
	s_waitcnt lgkmcnt(2)
	v_mfma_scale_f32_32x32x64_f8f6f4 v[82:97], v[82:89], v[146:153], v[230:245], v194, v193 op_sel_hi:[0,0,0]
	v_exp_f32_e32 v0, v118
	v_exp_f32_e32 v177, v119
	v_exp_f32_e32 v179, v120
	v_exp_f32_e32 v254, v121
	v_add_f32_e32 v219, v0, v219
	v_add_f32_e32 v219, v177, v219
	v_cvt_pk_fp8_f32 v247, v0, v177
	v_add_f32_e32 v219, v179, v219
	v_add_f32_e32 v219, v254, v219
	v_cvt_pk_fp8_f32 v247, v179, v254 op_sel:[0,0,1]
	ds_read_b128 v[114:117], v213 offset:24576
	ds_read_b128 v[118:121], v214 offset:24576
	s_waitcnt lgkmcnt(2)
	v_mfma_scale_f32_32x32x64_f8f6f4 v[66:81], v[222:229], v[146:153], v[230:245], v194, v193 op_sel_hi:[0,0,0]
	ds_read_b128 v[222:225], v213 offset:28672
	ds_read_b128 v[226:229], v214 offset:28672
	v_exp_f32_e32 v0, v122
	v_exp_f32_e32 v177, v123
	v_exp_f32_e32 v179, v124
	v_exp_f32_e32 v254, v125
	v_add_f32_e32 v219, v0, v219
	v_add_f32_e32 v219, v177, v219
	v_cvt_pk_fp8_f32 v248, v0, v177
	v_add_f32_e32 v219, v179, v219
	v_add_f32_e32 v219, v254, v219
	v_cvt_pk_fp8_f32 v248, v179, v254 op_sel:[0,0,1]
	v_exp_f32_e32 v0, v126
	v_exp_f32_e32 v177, v127
	v_exp_f32_e32 v179, v128
	v_exp_f32_e32 v254, v129
	v_add_f32_e32 v219, v0, v219
	v_add_f32_e32 v219, v177, v219
	v_cvt_pk_fp8_f32 v249, v0, v177
	v_add_f32_e32 v219, v179, v219
	v_add_f32_e32 v219, v254, v219
	v_cvt_pk_fp8_f32 v249, v179, v254 op_sel:[0,0,1]
	ds_read_b128 v[122:125], v185 offset:36864
	ds_read_b128 v[126:129], v186 offset:36864
	s_waitcnt lgkmcnt(4)
	v_mfma_scale_f32_32x32x64_f8f6f4 v[82:97], v[114:121], v[138:145], v[82:97], v194, v193 op_sel_hi:[0,0,0]
	v_exp_f32_e32 v0, v98
	v_exp_f32_e32 v177, v99
	v_exp_f32_e32 v179, v100
	v_exp_f32_e32 v254, v101
	v_add_f32_e32 v219, v0, v219
	v_add_f32_e32 v219, v177, v219
	v_cvt_pk_fp8_f32 v250, v0, v177
	v_add_f32_e32 v219, v179, v219
	v_add_f32_e32 v219, v254, v219
	v_cvt_pk_fp8_f32 v250, v179, v254 op_sel:[0,0,1]
	s_waitcnt lgkmcnt(2)
	v_mfma_scale_f32_32x32x64_f8f6f4 v[66:81], v[222:229], v[138:145], v[66:81], v194, v193 op_sel_hi:[0,0,0]
	ds_read_b128 v[222:225], v185 offset:38912
	ds_read_b128 v[226:229], v186 offset:38912
	v_exp_f32_e32 v0, v102
	v_exp_f32_e32 v177, v103
	v_exp_f32_e32 v179, v104
	v_exp_f32_e32 v254, v105
	v_add_f32_e32 v219, v0, v219
	v_add_f32_e32 v219, v177, v219
	v_cvt_pk_fp8_f32 v251, v0, v177
	v_add_f32_e32 v219, v179, v219
	v_add_f32_e32 v219, v254, v219
	v_cvt_pk_fp8_f32 v251, v179, v254 op_sel:[0,0,1]
	v_exp_f32_e32 v0, v106
	v_exp_f32_e32 v177, v107
	v_exp_f32_e32 v179, v108
	v_exp_f32_e32 v254, v109
	v_add_f32_e32 v219, v0, v219
	v_add_f32_e32 v219, v177, v219
	v_cvt_pk_fp8_f32 v252, v0, v177
	v_add_f32_e32 v219, v179, v219
	v_add_f32_e32 v219, v254, v219
	v_cvt_pk_fp8_f32 v252, v179, v254 op_sel:[0,0,1]
	s_waitcnt lgkmcnt(2)
	v_mfma_scale_f32_32x32x64_f8f6f4 v[82:97], v[122:129], v[130:137], v[82:97], v194, v193 op_sel_hi:[0,0,0]
	v_exp_f32_e32 v0, v110
	v_exp_f32_e32 v177, v111
	v_exp_f32_e32 v179, v112
	v_exp_f32_e32 v254, v113
	v_add_f32_e32 v219, v0, v219
	v_add_f32_e32 v219, v177, v219
	v_cvt_pk_fp8_f32 v253, v0, v177
	v_add_f32_e32 v219, v179, v219
	v_add_f32_e32 v219, v254, v219
	v_cvt_pk_fp8_f32 v253, v179, v254 op_sel:[0,0,1]
	ds_read_b128 v[122:125], v185 offset:0
	ds_read_b128 v[126:129], v186 offset:0
	ds_read_b128 v[114:117], v185 offset:2048
	ds_read_b128 v[118:121], v186 offset:2048
	ds_read_b128 v[106:109], v185 offset:4096
	ds_read_b128 v[110:113], v186 offset:4096
	ds_read_b128 v[98:101], v185 offset:6144
	ds_read_b128 v[102:105], v186 offset:6144
	s_waitcnt lgkmcnt(8)
	v_mfma_scale_f32_32x32x64_f8f6f4 v[66:81], v[222:229], v[130:137], v[66:81], v194, v193 op_sel_hi:[0,0,0]
	v_mov_b32_e32 v0, v219
	s_nop 1
	v_permlane32_swap_b32_e32 v219, v0
	v_add_f32_e32 v219, v219, v0
	v_fma_f32 v209, v209, v221, v219
	v_max_f32_e32 v177, v82, v83
	v_max3_f32 v177, v177, v84, v85
	v_max3_f32 v177, v177, v86, v87
	v_max3_f32 v177, v177, v88, v89
	v_max3_f32 v177, v177, v90, v91
	v_max3_f32 v177, v177, v92, v93
	v_max3_f32 v177, v177, v94, v95
	v_max3_f32 v177, v177, v96, v97
	s_waitcnt lgkmcnt(6)
	v_mfma_scale_f32_32x32x64_f8f6f4 v[50:65], v[246:253], v[122:129], v[50:65], v194, v194 op_sel_hi:[0,0,0]
	s_waitcnt vmcnt(0)
	ds_write_b128 v210, v[158:161] offset:43008
	ds_write_b128 v211, v[162:165] offset:51200
	s_waitcnt lgkmcnt(6)
	v_mfma_scale_f32_32x32x64_f8f6f4 v[34:49], v[246:253], v[114:121], v[34:49], v194, v194 op_sel_hi:[0,0,0]
	s_waitcnt lgkmcnt(0)
	s_barrier
	global_load_dwordx4 v[158:161], v176, s[18:19]
	global_load_dwordx4 v[162:165], v178, s[16:17]
	v_add_u32_e32 v176, 0x2000, v176
	v_add_u32_e32 v178, 0x20000, v178
	s_waitcnt lgkmcnt(2)
	v_mfma_scale_f32_32x32x64_f8f6f4 v[18:33], v[246:253], v[106:113], v[18:33], v194, v194 op_sel_hi:[0,0,0]
	s_waitcnt lgkmcnt(0)
	v_mfma_scale_f32_32x32x64_f8f6f4 v[2:17], v[246:253], v[98:105], v[2:17], v194, v194 op_sel_hi:[0,0,0]
	v_max_f32_e32 v0, v66, v67
	v_max3_f32 v0, v0, v68, v69
	v_max3_f32 v0, v0, v70, v71
	v_max3_f32 v0, v0, v72, v73
	v_max3_f32 v0, v0, v74, v75
	v_max3_f32 v0, v0, v76, v77
	v_max3_f32 v0, v0, v78, v79
	v_max3_f32 v0, v0, v80, v81
	v_max_f32_e32 v177, v177, v0
	v_mov_b32_e32 v0, v177
	v_mov_b32_e32 v218, 1.0
	s_nop 0
	v_permlane32_swap_b32_e32 v177, v0
	v_max_f32_e32 v177, v177, v0
	v_cmp_ge_f32_e32 vcc, s90, v177
	s_cmp_eq_u64 vcc, exec
	s_cbranch_scc0 .Lmla_s3_newmax
; __device__ __forceinline__ void finishSM9(f32x16& p0, f32x16& p1, float alpha, float& l_reg, v8i32& p8) {
; #pragma unroll
;   for (int r = 0; r < 16; ++r) { p0[r] = __builtin_amdgcn_exp2f(p0[r]); p1[r] = __builtin_amdgcn_exp2f(p1[r]); }
;   float ps = 0;
; #pragma unroll
;   for (int r = 0; r < 16; ++r) ps += p0[r];
; #pragma unroll
;   for (int r = 0; r < 16; ++r) ps += p1[r];
;   { auto rr = __builtin_amdgcn_permlane32_swap(__float_as_uint(ps), __float_as_uint(ps), false, false);
;     ps = __uint_as_float(rr[0]) + __uint_as_float(rr[1]); }
;   l_reg = l_reg * alpha + ps;
; #pragma unroll
;   for (int g = 0; g < 4; ++g) {
;     int w = __builtin_amdgcn_cvt_pk_fp8_f32(p0[4 * g], p0[4 * g + 1], 0, false); p8[g] = __builtin_amdgcn_cvt_pk_fp8_f32(p0[4 * g + 2], p0[4 * g + 3], w, true);
;     int u = __builtin_amdgcn_cvt_pk_fp8_f32(p1[4 * g], p1[4 * g + 1], 0, false); p8[4 + g] = __builtin_amdgcn_cvt_pk_fp8_f32(p1[4 * g + 2], p1[4 * g + 3], u, true); }
; }
; __device__ __forceinline__ void pv8(f32x16* o, const char* Vt, const v8i32 p8, int r32, int hi) {
;   const int sw = (r32 >> 2) & 3, a0 = r32 * 64 + (((hi * 2) ^ sw) << 4), a1 = r32 * 64 + (((hi * 2 + 1) ^ sw) << 4);
; #pragma unroll
;   for (int d0 = 0; d0 < 4; ++d0) {
;     const v8i32 vf = cat8(*reinterpret_cast<const v4i32*>(Vt + d0 * 2048 + a0), *reinterpret_cast<const v4i32*>(Vt + d0 * 2048 + a1));
;     o[d0] = __builtin_amdgcn_mfma_scale_f32_32x32x64_f8f6f4(p8, vf, o[d0], 0, 0, 0, 127, 0, 127); }
; }
; __device__ __forceinline__ void qkt9(f32x16& p0, f32x16& p1, const char* Kn, const char* Kr, const v8i32* qf, const float init, int r32, int hi) {
; #pragma unroll
;   for (int r = 0; r < 16; ++r) { p0[r] = init; p1[r] = init; }
; #pragma unroll
;   for (int s = 0; s < 2; ++s) { const int c0 = s * 4 + hi * 2;
;     const v8i32 a0 = cat8(*reinterpret_cast<const v4i32*>(Kn + KN8SW(r32, c0)), *reinterpret_cast<const v4i32*>(Kn + KN8SW(r32, c0 + 1)));
;     const v8i32 a1 = cat8(*reinterpret_cast<const v4i32*>(Kn + 4096 + KN8SW(r32, c0)), *reinterpret_cast<const v4i32*>(Kn + 4096 + KN8SW(r32, c0 + 1)));
;     p0 = __builtin_amdgcn_mfma_scale_f32_32x32x64_f8f6f4(a0, qf[s], p0, 0, 0, 0, 127, 0, 124);
;     p1 = __builtin_amdgcn_mfma_scale_f32_32x32x64_f8f6f4(a1, qf[s], p1, 0, 0, 0, 127, 0, 124); }
;   { const int c0 = hi * 2;
.Lmla_s3_cont:
	ds_read_b128 v[114:117], v215 offset:51200
	ds_read_b128 v[118:121], v216 offset:51200
	ds_read_b128 v[222:225], v215 offset:55296
	ds_read_b128 v[226:229], v216 offset:55296
	v_exp_f32_e32 v0, v82
	v_exp_f32_e32 v177, v83
	v_exp_f32_e32 v179, v84
	v_exp_f32_e32 v254, v85
	v_add_f32_e32 v219, v0, v177
	v_cvt_pk_fp8_f32 v246, v0, v177
	v_add_f32_e32 v219, v179, v219
	v_add_f32_e32 v219, v254, v219
	v_cvt_pk_fp8_f32 v246, v179, v254 op_sel:[0,0,1]
	s_waitcnt lgkmcnt(2)
	v_mfma_scale_f32_32x32x64_f8f6f4 v[114:129], v[114:121], v[146:153], v[230:245], v194, v193 op_sel_hi:[0,0,0]
	v_exp_f32_e32 v0, v86
	v_exp_f32_e32 v177, v87
	v_exp_f32_e32 v179, v88
	v_exp_f32_e32 v254, v89
	v_add_f32_e32 v219, v0, v219
	v_add_f32_e32 v219, v177, v219
	v_cvt_pk_fp8_f32 v247, v0, v177
	v_add_f32_e32 v219, v179, v219
	v_add_f32_e32 v219, v254, v219
	v_cvt_pk_fp8_f32 v247, v179, v254 op_sel:[0,0,1]
	ds_read_b128 v[82:85], v213 offset:51200
	ds_read_b128 v[86:89], v214 offset:51200
	s_waitcnt lgkmcnt(2)
	v_mfma_scale_f32_32x32x64_f8f6f4 v[98:113], v[222:229], v[146:153], v[230:245], v194, v193 op_sel_hi:[0,0,0]
	ds_read_b128 v[222:225], v213 offset:55296
	ds_read_b128 v[226:229], v214 offset:55296
	v_exp_f32_e32 v0, v90
	v_exp_f32_e32 v177, v91
	v_exp_f32_e32 v179, v92
	v_exp_f32_e32 v254, v93
	v_add_f32_e32 v219, v0, v219
	v_add_f32_e32 v219, v177, v219
	v_cvt_pk_fp8_f32 v248, v0, v177
	v_add_f32_e32 v219, v179, v219
	v_add_f32_e32 v219, v254, v219
	v_cvt_pk_fp8_f32 v248, v179, v254 op_sel:[0,0,1]
	v_exp_f32_e32 v0, v94
	v_exp_f32_e32 v177, v95
	v_exp_f32_e32 v179, v96
	v_exp_f32_e32 v254, v97
	v_add_f32_e32 v219, v0, v219
	v_add_f32_e32 v219, v177, v219
	v_cvt_pk_fp8_f32 v249, v0, v177
	v_add_f32_e32 v219, v179, v219
	v_add_f32_e32 v219, v254, v219
	v_cvt_pk_fp8_f32 v249, v179, v254 op_sel:[0,0,1]
	ds_read_b128 v[90:93], v185 offset:59392
	ds_read_b128 v[94:97], v186 offset:59392
	s_waitcnt lgkmcnt(4)
	v_mfma_scale_f32_32x32x64_f8f6f4 v[114:129], v[82:89], v[138:145], v[114:129], v194, v193 op_sel_hi:[0,0,0]
	v_exp_f32_e32 v0, v66
	v_exp_f32_e32 v177, v67
	v_exp_f32_e32 v179, v68
	v_exp_f32_e32 v254, v69
	v_add_f32_e32 v219, v0, v219
	v_add_f32_e32 v219, v177, v219
	v_cvt_pk_fp8_f32 v250, v0, v177
	v_add_f32_e32 v219, v179, v219
	v_add_f32_e32 v219, v254, v219
	v_cvt_pk_fp8_f32 v250, v179, v254 op_sel:[0,0,1]
	s_waitcnt lgkmcnt(2)
	v_mfma_scale_f32_32x32x64_f8f6f4 v[98:113], v[222:229], v[138:145], v[98:113], v194, v193 op_sel_hi:[0,0,0]
	ds_read_b128 v[222:225], v185 offset:61440
	ds_read_b128 v[226:229], v186 offset:61440
	v_exp_f32_e32 v0, v70
	v_exp_f32_e32 v177, v71
	v_exp_f32_e32 v179, v72
	v_exp_f32_e32 v254, v73
	v_add_f32_e32 v219, v0, v219
	v_add_f32_e32 v219, v177, v219
	v_cvt_pk_fp8_f32 v251, v0, v177
	v_add_f32_e32 v219, v179, v219
	v_add_f32_e32 v219, v254, v219
	v_cvt_pk_fp8_f32 v251, v179, v254 op_sel:[0,0,1]
	v_exp_f32_e32 v0, v74
	v_exp_f32_e32 v177, v75
	v_exp_f32_e32 v179, v76
	v_exp_f32_e32 v254, v77
	v_add_f32_e32 v219, v0, v219
	v_add_f32_e32 v219, v177, v219
	v_cvt_pk_fp8_f32 v252, v0, v177
	v_add_f32_e32 v219, v179, v219
	v_add_f32_e32 v219, v254, v219
	v_cvt_pk_fp8_f32 v252, v179, v254 op_sel:[0,0,1]
	s_waitcnt lgkmcnt(2)
	v_mfma_scale_f32_32x32x64_f8f6f4 v[114:129], v[90:97], v[130:137], v[114:129], v194, v193 op_sel_hi:[0,0,0]
	v_exp_f32_e32 v0, v78
	v_exp_f32_e32 v177, v79
	v_exp_f32_e32 v179, v80
	v_exp_f32_e32 v254, v81
	v_add_f32_e32 v219, v0, v219
	v_add_f32_e32 v219, v177, v219
	v_cvt_pk_fp8_f32 v253, v0, v177
	v_add_f32_e32 v219, v179, v219
	v_add_f32_e32 v219, v254, v219
	v_cvt_pk_fp8_f32 v253, v179, v254 op_sel:[0,0,1]
	ds_read_b128 v[90:93], v185 offset:8192
	ds_read_b128 v[94:97], v186 offset:8192
	ds_read_b128 v[82:85], v185 offset:10240
	ds_read_b128 v[86:89], v186 offset:10240
	ds_read_b128 v[74:77], v185 offset:12288
	ds_read_b128 v[78:81], v186 offset:12288
	ds_read_b128 v[66:69], v185 offset:14336
	ds_read_b128 v[70:73], v186 offset:14336
	s_waitcnt lgkmcnt(8)
	v_mfma_scale_f32_32x32x64_f8f6f4 v[98:113], v[222:229], v[130:137], v[98:113], v194, v193 op_sel_hi:[0,0,0]
	v_mov_b32_e32 v0, v219
	s_nop 1
	v_permlane32_swap_b32_e32 v219, v0
	v_add_f32_e32 v219, v219, v0
	v_fma_f32 v209, v209, v218, v219
	v_max_f32_e32 v177, v114, v115
	v_max3_f32 v177, v177, v116, v117
	v_max3_f32 v177, v177, v118, v119
	v_max3_f32 v177, v177, v120, v121
	v_max3_f32 v177, v177, v122, v123
	v_max3_f32 v177, v177, v124, v125
	v_max3_f32 v177, v177, v126, v127
	v_max3_f32 v177, v177, v128, v129
	s_waitcnt lgkmcnt(6)
	v_mfma_scale_f32_32x32x64_f8f6f4 v[50:65], v[246:253], v[90:97], v[50:65], v194, v194 op_sel_hi:[0,0,0]
	s_waitcnt vmcnt(0)
	ds_write_b128 v210, v[158:161]
	ds_write_b128 v211, v[162:165] offset:16384
	s_waitcnt lgkmcnt(6)
	v_mfma_scale_f32_32x32x64_f8f6f4 v[34:49], v[246:253], v[82:89], v[34:49], v194, v194 op_sel_hi:[0,0,0]
	s_waitcnt lgkmcnt(0)
	s_barrier
	global_load_dwordx4 v[158:161], v176, s[18:19]
	global_load_dwordx4 v[162:165], v178, s[16:17]
	v_add_u32_e32 v176, 0x2000, v176
	v_add_u32_e32 v178, 0x20000, v178
	s_waitcnt lgkmcnt(2)
	v_mfma_scale_f32_32x32x64_f8f6f4 v[18:33], v[246:253], v[74:81], v[18:33], v194, v194 op_sel_hi:[0,0,0]
	s_waitcnt lgkmcnt(0)
	v_mfma_scale_f32_32x32x64_f8f6f4 v[2:17], v[246:253], v[66:73], v[2:17], v194, v194 op_sel_hi:[0,0,0]
	v_max_f32_e32 v0, v98, v99
	v_max3_f32 v0, v0, v100, v101
	v_max3_f32 v0, v0, v102, v103
	v_max3_f32 v0, v0, v104, v105
	v_max3_f32 v0, v0, v106, v107
	v_max3_f32 v0, v0, v108, v109
	v_max3_f32 v0, v0, v110, v111
	v_max3_f32 v0, v0, v112, v113
	v_max_f32_e32 v177, v177, v0
	v_mov_b32_e32 v0, v177
	v_mov_b32_e32 v221, 1.0
	s_nop 0
	v_permlane32_swap_b32_e32 v177, v0
	v_max_f32_e32 v177, v177, v0
	v_cmp_ge_f32_e32 vcc, s90, v177
	s_cmp_eq_u64 vcc, exec
	s_cbranch_scc0 .Lmla_s4_newmax
; __device__ __forceinline__ void finishSM9(f32x16& p0, f32x16& p1, float alpha, float& l_reg, v8i32& p8) {
; #pragma unroll
;   for (int r = 0; r < 16; ++r) { p0[r] = __builtin_amdgcn_exp2f(p0[r]); p1[r] = __builtin_amdgcn_exp2f(p1[r]); }
;   float ps = 0;
; #pragma unroll
;   for (int r = 0; r < 16; ++r) ps += p0[r];
; #pragma unroll
;   for (int r = 0; r < 16; ++r) ps += p1[r];
;   { auto rr = __builtin_amdgcn_permlane32_swap(__float_as_uint(ps), __float_as_uint(ps), false, false);
;     ps = __uint_as_float(rr[0]) + __uint_as_float(rr[1]); }
;   l_reg = l_reg * alpha + ps;
; #pragma unroll
;   for (int g = 0; g < 4; ++g) {
;     int w = __builtin_amdgcn_cvt_pk_fp8_f32(p0[4 * g], p0[4 * g + 1], 0, false); p8[g] = __builtin_amdgcn_cvt_pk_fp8_f32(p0[4 * g + 2], p0[4 * g + 3], w, true);
;     int u = __builtin_amdgcn_cvt_pk_fp8_f32(p1[4 * g], p1[4 * g + 1], 0, false); p8[4 + g] = __builtin_amdgcn_cvt_pk_fp8_f32(p1[4 * g + 2], p1[4 * g + 3], u, true); }
; }
; __device__ __forceinline__ void pv8(f32x16* o, const char* Vt, const v8i32 p8, int r32, int hi) {
;   const int sw = (r32 >> 2) & 3, a0 = r32 * 64 + (((hi * 2) ^ sw) << 4), a1 = r32 * 64 + (((hi * 2 + 1) ^ sw) << 4);
; #pragma unroll
;   for (int d0 = 0; d0 < 4; ++d0) {
;     const v8i32 vf = cat8(*reinterpret_cast<const v4i32*>(Vt + d0 * 2048 + a0), *reinterpret_cast<const v4i32*>(Vt + d0 * 2048 + a1));
;     o[d0] = __builtin_amdgcn_mfma_scale_f32_32x32x64_f8f6f4(p8, vf, o[d0], 0, 0, 0, 127, 0, 127); }
; }
; __device__ __forceinline__ void qkt9(f32x16& p0, f32x16& p1, const char* Kn, const char* Kr, const v8i32* qf, const float init, int r32, int hi) {
; #pragma unroll
;   for (int r = 0; r < 16; ++r) { p0[r] = init; p1[r] = init; }
; #pragma unroll
;   for (int s = 0; s < 2; ++s) { const int c0 = s * 4 + hi * 2;
;     const v8i32 a0 = cat8(*reinterpret_cast<const v4i32*>(Kn + KN8SW(r32, c0)), *reinterpret_cast<const v4i32*>(Kn + KN8SW(r32, c0 + 1)));
;     const v8i32 a1 = cat8(*reinterpret_cast<const v4i32*>(Kn + 4096 + KN8SW(r32, c0)), *reinterpret_cast<const v4i32*>(Kn + 4096 + KN8SW(r32, c0 + 1)));
;     p0 = __builtin_amdgcn_mfma_scale_f32_32x32x64_f8f6f4(a0, qf[s], p0, 0, 0, 0, 127, 0, 124);
;     p1 = __builtin_amdgcn_mfma_scale_f32_32x32x64_f8f6f4(a1, qf[s], p1, 0, 0, 0, 127, 0, 124); }
;   { const int c0 = hi * 2;
.Lmla_s4_cont:
	ds_read_b128 v[82:85], v215 offset:16384
	ds_read_b128 v[86:89], v216 offset:16384
	ds_read_b128 v[222:225], v215 offset:20480
	ds_read_b128 v[226:229], v216 offset:20480
	v_exp_f32_e32 v0, v114
	v_exp_f32_e32 v177, v115
	v_exp_f32_e32 v179, v116
	v_exp_f32_e32 v254, v117
	v_add_f32_e32 v219, v0, v177
	v_cvt_pk_fp8_f32 v246, v0, v177
	v_add_f32_e32 v219, v179, v219
	v_add_f32_e32 v219, v254, v219
	v_cvt_pk_fp8_f32 v246, v179, v254 op_sel:[0,0,1]
	s_waitcnt lgkmcnt(2)
	v_mfma_scale_f32_32x32x64_f8f6f4 v[82:97], v[82:89], v[146:153], v[230:245], v194, v193 op_sel_hi:[0,0,0]
	v_exp_f32_e32 v0, v118
	v_exp_f32_e32 v177, v119
	v_exp_f32_e32 v179, v120
	v_exp_f32_e32 v254, v121
	v_add_f32_e32 v219, v0, v219
	v_add_f32_e32 v219, v177, v219
	v_cvt_pk_fp8_f32 v247, v0, v177
	v_add_f32_e32 v219, v179, v219
	v_add_f32_e32 v219, v254, v219
	v_cvt_pk_fp8_f32 v247, v179, v254 op_sel:[0,0,1]
	ds_read_b128 v[114:117], v213 offset:16384
	ds_read_b128 v[118:121], v214 offset:16384
	s_waitcnt lgkmcnt(2)
	v_mfma_scale_f32_32x32x64_f8f6f4 v[66:81], v[222:229], v[146:153], v[230:245], v194, v193 op_sel_hi:[0,0,0]
	ds_read_b128 v[222:225], v213 offset:20480
	ds_read_b128 v[226:229], v214 offset:20480
	v_exp_f32_e32 v0, v122
	v_exp_f32_e32 v177, v123
	v_exp_f32_e32 v179, v124
	v_exp_f32_e32 v254, v125
	v_add_f32_e32 v219, v0, v219
	v_add_f32_e32 v219, v177, v219
	v_cvt_pk_fp8_f32 v248, v0, v177
	v_add_f32_e32 v219, v179, v219
	v_add_f32_e32 v219, v254, v219
	v_cvt_pk_fp8_f32 v248, v179, v254 op_sel:[0,0,1]
	v_exp_f32_e32 v0, v126
	v_exp_f32_e32 v177, v127
	v_exp_f32_e32 v179, v128
	v_exp_f32_e32 v254, v129
	v_add_f32_e32 v219, v0, v219
	v_add_f32_e32 v219, v177, v219
	v_cvt_pk_fp8_f32 v249, v0, v177
	v_add_f32_e32 v219, v179, v219
	v_add_f32_e32 v219, v254, v219
	v_cvt_pk_fp8_f32 v249, v179, v254 op_sel:[0,0,1]
	ds_read_b128 v[122:125], v185 offset:32768
	ds_read_b128 v[126:129], v186 offset:32768
	s_waitcnt lgkmcnt(4)
	v_mfma_scale_f32_32x32x64_f8f6f4 v[82:97], v[114:121], v[138:145], v[82:97], v194, v193 op_sel_hi:[0,0,0]
	v_exp_f32_e32 v0, v98
	v_exp_f32_e32 v177, v99
	v_exp_f32_e32 v179, v100
	v_exp_f32_e32 v254, v101
	v_add_f32_e32 v219, v0, v219
	v_add_f32_e32 v219, v177, v219
	v_cvt_pk_fp8_f32 v250, v0, v177
	v_add_f32_e32 v219, v179, v219
	v_add_f32_e32 v219, v254, v219
	v_cvt_pk_fp8_f32 v250, v179, v254 op_sel:[0,0,1]
	s_waitcnt lgkmcnt(2)
	v_mfma_scale_f32_32x32x64_f8f6f4 v[66:81], v[222:229], v[138:145], v[66:81], v194, v193 op_sel_hi:[0,0,0]
	ds_read_b128 v[222:225], v185 offset:34816
	ds_read_b128 v[226:229], v186 offset:34816
	v_exp_f32_e32 v0, v102
	v_exp_f32_e32 v177, v103
	v_exp_f32_e32 v179, v104
	v_exp_f32_e32 v254, v105
	v_add_f32_e32 v219, v0, v219
	v_add_f32_e32 v219, v177, v219
	v_cvt_pk_fp8_f32 v251, v0, v177
	v_add_f32_e32 v219, v179, v219
	v_add_f32_e32 v219, v254, v219
	v_cvt_pk_fp8_f32 v251, v179, v254 op_sel:[0,0,1]
	v_exp_f32_e32 v0, v106
	v_exp_f32_e32 v177, v107
	v_exp_f32_e32 v179, v108
	v_exp_f32_e32 v254, v109
	v_add_f32_e32 v219, v0, v219
	v_add_f32_e32 v219, v177, v219
	v_cvt_pk_fp8_f32 v252, v0, v177
	v_add_f32_e32 v219, v179, v219
	v_add_f32_e32 v219, v254, v219
	v_cvt_pk_fp8_f32 v252, v179, v254 op_sel:[0,0,1]
	s_waitcnt lgkmcnt(2)
	v_mfma_scale_f32_32x32x64_f8f6f4 v[82:97], v[122:129], v[130:137], v[82:97], v194, v193 op_sel_hi:[0,0,0]
	v_exp_f32_e32 v0, v110
	v_exp_f32_e32 v177, v111
	v_exp_f32_e32 v179, v112
	v_exp_f32_e32 v254, v113
	v_add_f32_e32 v219, v0, v219
	v_add_f32_e32 v219, v177, v219
	v_cvt_pk_fp8_f32 v253, v0, v177
	v_add_f32_e32 v219, v179, v219
	v_add_f32_e32 v219, v254, v219
	v_cvt_pk_fp8_f32 v253, v179, v254 op_sel:[0,0,1]
	ds_read_b128 v[122:125], v185 offset:43008
	ds_read_b128 v[126:129], v186 offset:43008
	ds_read_b128 v[114:117], v185 offset:45056
	ds_read_b128 v[118:121], v186 offset:45056
	ds_read_b128 v[106:109], v185 offset:47104
	ds_read_b128 v[110:113], v186 offset:47104
	ds_read_b128 v[98:101], v185 offset:49152
	ds_read_b128 v[102:105], v186 offset:49152
	s_waitcnt lgkmcnt(8)
	v_mfma_scale_f32_32x32x64_f8f6f4 v[66:81], v[222:229], v[130:137], v[66:81], v194, v193 op_sel_hi:[0,0,0]
	v_mov_b32_e32 v0, v219
	s_nop 1
	v_permlane32_swap_b32_e32 v219, v0
	v_add_f32_e32 v219, v219, v0
	v_fma_f32 v209, v209, v221, v219
	v_max_f32_e32 v177, v82, v83
	v_max3_f32 v177, v177, v84, v85
	v_max3_f32 v177, v177, v86, v87
	v_max3_f32 v177, v177, v88, v89
	v_max3_f32 v177, v177, v90, v91
	v_max3_f32 v177, v177, v92, v93
	v_max3_f32 v177, v177, v94, v95
	v_max3_f32 v177, v177, v96, v97
	s_waitcnt lgkmcnt(6)
	v_mfma_scale_f32_32x32x64_f8f6f4 v[50:65], v[246:253], v[122:129], v[50:65], v194, v194 op_sel_hi:[0,0,0]
	s_waitcnt vmcnt(0)
	ds_write_b128 v210, v[158:161] offset:8192
	ds_write_b128 v211, v[162:165] offset:24576
	s_waitcnt lgkmcnt(6)
	v_mfma_scale_f32_32x32x64_f8f6f4 v[34:49], v[246:253], v[114:121], v[34:49], v194, v194 op_sel_hi:[0,0,0]
	s_waitcnt lgkmcnt(0)
	s_barrier
	global_load_dwordx4 v[158:161], v176, s[18:19]
	global_load_dwordx4 v[162:165], v178, s[16:17]
	v_add_u32_e32 v176, 0x2000, v176
	v_add_u32_e32 v178, 0x20000, v178
	s_waitcnt lgkmcnt(2)
	v_mfma_scale_f32_32x32x64_f8f6f4 v[18:33], v[246:253], v[106:113], v[18:33], v194, v194 op_sel_hi:[0,0,0]
	s_waitcnt lgkmcnt(0)
	v_mfma_scale_f32_32x32x64_f8f6f4 v[2:17], v[246:253], v[98:105], v[2:17], v194, v194 op_sel_hi:[0,0,0]
	v_max_f32_e32 v0, v66, v67
	v_max3_f32 v0, v0, v68, v69
	v_max3_f32 v0, v0, v70, v71
	v_max3_f32 v0, v0, v72, v73
	v_max3_f32 v0, v0, v74, v75
	v_max3_f32 v0, v0, v76, v77
	v_max3_f32 v0, v0, v78, v79
	v_max3_f32 v0, v0, v80, v81
	v_max_f32_e32 v177, v177, v0
	v_mov_b32_e32 v0, v177
	v_mov_b32_e32 v218, 1.0
	s_nop 0
	v_permlane32_swap_b32_e32 v177, v0
	v_max_f32_e32 v177, v177, v0
	v_cmp_ge_f32_e32 vcc, s90, v177
	s_cmp_eq_u64 vcc, exec
	s_cbranch_scc0 .Lmla_s5_newmax
; __device__ __forceinline__ void finishSM9(f32x16& p0, f32x16& p1, float alpha, float& l_reg, v8i32& p8) {
; #pragma unroll
;   for (int r = 0; r < 16; ++r) { p0[r] = __builtin_amdgcn_exp2f(p0[r]); p1[r] = __builtin_amdgcn_exp2f(p1[r]); }
;   float ps = 0;
; #pragma unroll
;   for (int r = 0; r < 16; ++r) ps += p0[r];
; #pragma unroll
;   for (int r = 0; r < 16; ++r) ps += p1[r];
;   { auto rr = __builtin_amdgcn_permlane32_swap(__float_as_uint(ps), __float_as_uint(ps), false, false);
;     ps = __uint_as_float(rr[0]) + __uint_as_float(rr[1]); }
;   l_reg = l_reg * alpha + ps;
; #pragma unroll
;   for (int g = 0; g < 4; ++g) {
;     int w = __builtin_amdgcn_cvt_pk_fp8_f32(p0[4 * g], p0[4 * g + 1], 0, false); p8[g] = __builtin_amdgcn_cvt_pk_fp8_f32(p0[4 * g + 2], p0[4 * g + 3], w, true);
;     int u = __builtin_amdgcn_cvt_pk_fp8_f32(p1[4 * g], p1[4 * g + 1], 0, false); p8[4 + g] = __builtin_amdgcn_cvt_pk_fp8_f32(p1[4 * g + 2], p1[4 * g + 3], u, true); }
; }
; __device__ __forceinline__ void pv8(f32x16* o, const char* Vt, const v8i32 p8, int r32, int hi) {
;   const int sw = (r32 >> 2) & 3, a0 = r32 * 64 + (((hi * 2) ^ sw) << 4), a1 = r32 * 64 + (((hi * 2 + 1) ^ sw) << 4);
; #pragma unroll
;   for (int d0 = 0; d0 < 4; ++d0) {
;     const v8i32 vf = cat8(*reinterpret_cast<const v4i32*>(Vt + d0 * 2048 + a0), *reinterpret_cast<const v4i32*>(Vt + d0 * 2048 + a1));
;     o[d0] = __builtin_amdgcn_mfma_scale_f32_32x32x64_f8f6f4(p8, vf, o[d0], 0, 0, 0, 127, 0, 127); }
; }
; __device__ __forceinline__ void qkt9(f32x16& p0, f32x16& p1, const char* Kn, const char* Kr, const v8i32* qf, const float init, int r32, int hi) {
; #pragma unroll
;   for (int r = 0; r < 16; ++r) { p0[r] = init; p1[r] = init; }
; #pragma unroll
;   for (int s = 0; s < 2; ++s) { const int c0 = s * 4 + hi * 2;
;     const v8i32 a0 = cat8(*reinterpret_cast<const v4i32*>(Kn + KN8SW(r32, c0)), *reinterpret_cast<const v4i32*>(Kn + KN8SW(r32, c0 + 1)));
;     const v8i32 a1 = cat8(*reinterpret_cast<const v4i32*>(Kn + 4096 + KN8SW(r32, c0)), *reinterpret_cast<const v4i32*>(Kn + 4096 + KN8SW(r32, c0 + 1)));
;     p0 = __builtin_amdgcn_mfma_scale_f32_32x32x64_f8f6f4(a0, qf[s], p0, 0, 0, 0, 127, 0, 124);
;     p1 = __builtin_amdgcn_mfma_scale_f32_32x32x64_f8f6f4(a1, qf[s], p1, 0, 0, 0, 127, 0, 124); }
;   { const int c0 = hi * 2;
.Lmla_s5_cont:
	s_add_i32 s30, s30, 1
	s_cmpk_lt_u32 s30, 42
	s_cbranch_scc1 .Lmla_stag_loop
	ds_read_b128 v[114:117], v215 offset:24576
	ds_read_b128 v[118:121], v216 offset:24576
	ds_read_b128 v[222:225], v215 offset:28672
	ds_read_b128 v[226:229], v216 offset:28672
	v_exp_f32_e32 v0, v82
	v_exp_f32_e32 v177, v83
	v_exp_f32_e32 v179, v84
	v_exp_f32_e32 v254, v85
	v_add_f32_e32 v219, v0, v177
	v_cvt_pk_fp8_f32 v246, v0, v177
	v_add_f32_e32 v219, v179, v219
	v_add_f32_e32 v219, v254, v219
	v_cvt_pk_fp8_f32 v246, v179, v254 op_sel:[0,0,1]
	s_waitcnt lgkmcnt(2)
	v_mfma_scale_f32_32x32x64_f8f6f4 v[114:129], v[114:121], v[146:153], v[230:245], v194, v193 op_sel_hi:[0,0,0]
	v_exp_f32_e32 v0, v86
	v_exp_f32_e32 v177, v87
	v_exp_f32_e32 v179, v88
	v_exp_f32_e32 v254, v89
	v_add_f32_e32 v219, v0, v219
	v_add_f32_e32 v219, v177, v219
	v_cvt_pk_fp8_f32 v247, v0, v177
	v_add_f32_e32 v219, v179, v219
	v_add_f32_e32 v219, v254, v219
	v_cvt_pk_fp8_f32 v247, v179, v254 op_sel:[0,0,1]
	ds_read_b128 v[82:85], v213 offset:24576
	ds_read_b128 v[86:89], v214 offset:24576
	s_waitcnt lgkmcnt(2)
	v_mfma_scale_f32_32x32x64_f8f6f4 v[98:113], v[222:229], v[146:153], v[230:245], v194, v193 op_sel_hi:[0,0,0]
	ds_read_b128 v[222:225], v213 offset:28672
	ds_read_b128 v[226:229], v214 offset:28672
	v_exp_f32_e32 v0, v90
	v_exp_f32_e32 v177, v91
	v_exp_f32_e32 v179, v92
	v_exp_f32_e32 v254, v93
	v_add_f32_e32 v219, v0, v219
	v_add_f32_e32 v219, v177, v219
	v_cvt_pk_fp8_f32 v248, v0, v177
	v_add_f32_e32 v219, v179, v219
	v_add_f32_e32 v219, v254, v219
	v_cvt_pk_fp8_f32 v248, v179, v254 op_sel:[0,0,1]
	v_exp_f32_e32 v0, v94
	v_exp_f32_e32 v177, v95
	v_exp_f32_e32 v179, v96
	v_exp_f32_e32 v254, v97
	v_add_f32_e32 v219, v0, v219
	v_add_f32_e32 v219, v177, v219
	v_cvt_pk_fp8_f32 v249, v0, v177
	v_add_f32_e32 v219, v179, v219
	v_add_f32_e32 v219, v254, v219
	v_cvt_pk_fp8_f32 v249, v179, v254 op_sel:[0,0,1]
	ds_read_b128 v[90:93], v185 offset:36864
	ds_read_b128 v[94:97], v186 offset:36864
	s_waitcnt lgkmcnt(4)
	v_mfma_scale_f32_32x32x64_f8f6f4 v[114:129], v[82:89], v[138:145], v[114:129], v194, v193 op_sel_hi:[0,0,0]
	v_exp_f32_e32 v0, v66
	v_exp_f32_e32 v177, v67
	v_exp_f32_e32 v179, v68
	v_exp_f32_e32 v254, v69
	v_add_f32_e32 v219, v0, v219
	v_add_f32_e32 v219, v177, v219
	v_cvt_pk_fp8_f32 v250, v0, v177
	v_add_f32_e32 v219, v179, v219
	v_add_f32_e32 v219, v254, v219
	v_cvt_pk_fp8_f32 v250, v179, v254 op_sel:[0,0,1]
	s_waitcnt lgkmcnt(2)
	v_mfma_scale_f32_32x32x64_f8f6f4 v[98:113], v[222:229], v[138:145], v[98:113], v194, v193 op_sel_hi:[0,0,0]
	ds_read_b128 v[222:225], v185 offset:38912
	ds_read_b128 v[226:229], v186 offset:38912
	v_exp_f32_e32 v0, v70
	v_exp_f32_e32 v177, v71
	v_exp_f32_e32 v179, v72
	v_exp_f32_e32 v254, v73
	v_add_f32_e32 v219, v0, v219
	v_add_f32_e32 v219, v177, v219
	v_cvt_pk_fp8_f32 v251, v0, v177
	v_add_f32_e32 v219, v179, v219
	v_add_f32_e32 v219, v254, v219
	v_cvt_pk_fp8_f32 v251, v179, v254 op_sel:[0,0,1]
	v_exp_f32_e32 v0, v74
	v_exp_f32_e32 v177, v75
	v_exp_f32_e32 v179, v76
	v_exp_f32_e32 v254, v77
	v_add_f32_e32 v219, v0, v219
	v_add_f32_e32 v219, v177, v219
	v_cvt_pk_fp8_f32 v252, v0, v177
	v_add_f32_e32 v219, v179, v219
	v_add_f32_e32 v219, v254, v219
	v_cvt_pk_fp8_f32 v252, v179, v254 op_sel:[0,0,1]
	s_waitcnt lgkmcnt(2)
	v_mfma_scale_f32_32x32x64_f8f6f4 v[114:129], v[90:97], v[130:137], v[114:129], v194, v193 op_sel_hi:[0,0,0]
	v_exp_f32_e32 v0, v78
	v_exp_f32_e32 v177, v79
	v_exp_f32_e32 v179, v80
	v_exp_f32_e32 v254, v81
	v_add_f32_e32 v219, v0, v219
	v_add_f32_e32 v219, v177, v219
	v_cvt_pk_fp8_f32 v253, v0, v177
	v_add_f32_e32 v219, v179, v219
	v_add_f32_e32 v219, v254, v219
	v_cvt_pk_fp8_f32 v253, v179, v254 op_sel:[0,0,1]
	ds_read_b128 v[90:93], v185 offset:0
	ds_read_b128 v[94:97], v186 offset:0
	ds_read_b128 v[82:85], v185 offset:2048
	ds_read_b128 v[86:89], v186 offset:2048
	ds_read_b128 v[74:77], v185 offset:4096
	ds_read_b128 v[78:81], v186 offset:4096
	ds_read_b128 v[66:69], v185 offset:6144
	ds_read_b128 v[70:73], v186 offset:6144
	s_waitcnt lgkmcnt(8)
	v_mfma_scale_f32_32x32x64_f8f6f4 v[98:113], v[222:229], v[130:137], v[98:113], v194, v193 op_sel_hi:[0,0,0]
	v_mov_b32_e32 v0, v219
	s_nop 1
	v_permlane32_swap_b32_e32 v219, v0
	v_add_f32_e32 v219, v219, v0
	v_fma_f32 v209, v209, v218, v219
	v_max_f32_e32 v177, v114, v115
	v_max3_f32 v177, v177, v116, v117
	v_max3_f32 v177, v177, v118, v119
	v_max3_f32 v177, v177, v120, v121
	v_max3_f32 v177, v177, v122, v123
	v_max3_f32 v177, v177, v124, v125
	v_max3_f32 v177, v177, v126, v127
	v_max3_f32 v177, v177, v128, v129
	s_waitcnt lgkmcnt(6)
	v_mfma_scale_f32_32x32x64_f8f6f4 v[50:65], v[246:253], v[90:97], v[50:65], v194, v194 op_sel_hi:[0,0,0]
	s_waitcnt vmcnt(0)
	ds_write_b128 v210, v[158:161] offset:43008
	ds_write_b128 v211, v[162:165] offset:51200
	s_waitcnt lgkmcnt(6)
	v_mfma_scale_f32_32x32x64_f8f6f4 v[34:49], v[246:253], v[82:89], v[34:49], v194, v194 op_sel_hi:[0,0,0]
	s_waitcnt lgkmcnt(0)
	s_barrier
	global_load_dwordx4 v[158:161], v176, s[18:19]
	global_load_dwordx4 v[162:165], v178, s[16:17]
	v_add_u32_e32 v176, 0x2000, v176
	v_add_u32_e32 v178, 0x20000, v178
	s_waitcnt lgkmcnt(2)
	v_mfma_scale_f32_32x32x64_f8f6f4 v[18:33], v[246:253], v[74:81], v[18:33], v194, v194 op_sel_hi:[0,0,0]
	s_waitcnt lgkmcnt(0)
	v_mfma_scale_f32_32x32x64_f8f6f4 v[2:17], v[246:253], v[66:73], v[2:17], v194, v194 op_sel_hi:[0,0,0]
	v_max_f32_e32 v0, v98, v99
	v_max3_f32 v0, v0, v100, v101
	v_max3_f32 v0, v0, v102, v103
	v_max3_f32 v0, v0, v104, v105
	v_max3_f32 v0, v0, v106, v107
	v_max3_f32 v0, v0, v108, v109
	v_max3_f32 v0, v0, v110, v111
	v_max3_f32 v0, v0, v112, v113
	v_max_f32_e32 v177, v177, v0
	v_mov_b32_e32 v0, v177
	v_mov_b32_e32 v221, 1.0
	s_nop 0
	v_permlane32_swap_b32_e32 v177, v0
	v_max_f32_e32 v177, v177, v0
	v_cmp_ge_f32_e32 vcc, s90, v177
	s_cmp_eq_u64 vcc, exec
	s_cbranch_scc0 .Lmla_q0_newmax
; __device__ __forceinline__ void finishSM9(f32x16& p0, f32x16& p1, float alpha, float& l_reg, v8i32& p8) {
; #pragma unroll
;   for (int r = 0; r < 16; ++r) { p0[r] = __builtin_amdgcn_exp2f(p0[r]); p1[r] = __builtin_amdgcn_exp2f(p1[r]); }
;   float ps = 0;
; #pragma unroll
;   for (int r = 0; r < 16; ++r) ps += p0[r];
; #pragma unroll
;   for (int r = 0; r < 16; ++r) ps += p1[r];
;   { auto rr = __builtin_amdgcn_permlane32_swap(__float_as_uint(ps), __float_as_uint(ps), false, false);
;     ps = __uint_as_float(rr[0]) + __uint_as_float(rr[1]); }
;   l_reg = l_reg * alpha + ps;
; #pragma unroll
;   for (int g = 0; g < 4; ++g) {
;     int w = __builtin_amdgcn_cvt_pk_fp8_f32(p0[4 * g], p0[4 * g + 1], 0, false); p8[g] = __builtin_amdgcn_cvt_pk_fp8_f32(p0[4 * g + 2], p0[4 * g + 3], w, true);
;     int u = __builtin_amdgcn_cvt_pk_fp8_f32(p1[4 * g], p1[4 * g + 1], 0, false); p8[4 + g] = __builtin_amdgcn_cvt_pk_fp8_f32(p1[4 * g + 2], p1[4 * g + 3], u, true); }
; }
; __device__ __forceinline__ void pv8(f32x16* o, const char* Vt, const v8i32 p8, int r32, int hi) {
;   const int sw = (r32 >> 2) & 3, a0 = r32 * 64 + (((hi * 2) ^ sw) << 4), a1 = r32 * 64 + (((hi * 2 + 1) ^ sw) << 4);
; #pragma unroll
;   for (int d0 = 0; d0 < 4; ++d0) {
;     const v8i32 vf = cat8(*reinterpret_cast<const v4i32*>(Vt + d0 * 2048 + a0), *reinterpret_cast<const v4i32*>(Vt + d0 * 2048 + a1));
;     o[d0] = __builtin_amdgcn_mfma_scale_f32_32x32x64_f8f6f4(p8, vf, o[d0], 0, 0, 0, 127, 0, 127); }
; }
; __device__ __forceinline__ void qkt9(f32x16& p0, f32x16& p1, const char* Kn, const char* Kr, const v8i32* qf, const float init, int r32, int hi) {
; #pragma unroll
;   for (int r = 0; r < 16; ++r) { p0[r] = init; p1[r] = init; }
; #pragma unroll
;   for (int s = 0; s < 2; ++s) { const int c0 = s * 4 + hi * 2;
;     const v8i32 a0 = cat8(*reinterpret_cast<const v4i32*>(Kn + KN8SW(r32, c0)), *reinterpret_cast<const v4i32*>(Kn + KN8SW(r32, c0 + 1)));
;     const v8i32 a1 = cat8(*reinterpret_cast<const v4i32*>(Kn + 4096 + KN8SW(r32, c0)), *reinterpret_cast<const v4i32*>(Kn + 4096 + KN8SW(r32, c0 + 1)));
;     p0 = __builtin_amdgcn_mfma_scale_f32_32x32x64_f8f6f4(a0, qf[s], p0, 0, 0, 0, 127, 0, 124);
;     p1 = __builtin_amdgcn_mfma_scale_f32_32x32x64_f8f6f4(a1, qf[s], p1, 0, 0, 0, 127, 0, 124); }
;   { const int c0 = hi * 2;
.Lmla_q0_cont:
	ds_read_b128 v[82:85], v215 offset:51200
	ds_read_b128 v[86:89], v216 offset:51200
	ds_read_b128 v[222:225], v215 offset:55296
	ds_read_b128 v[226:229], v216 offset:55296
	v_exp_f32_e32 v0, v114
	v_exp_f32_e32 v177, v115
	v_exp_f32_e32 v179, v116
	v_exp_f32_e32 v254, v117
	v_add_f32_e32 v219, v0, v177
	v_cvt_pk_fp8_f32 v246, v0, v177
	v_add_f32_e32 v219, v179, v219
	v_add_f32_e32 v219, v254, v219
	v_cvt_pk_fp8_f32 v246, v179, v254 op_sel:[0,0,1]
	s_waitcnt lgkmcnt(2)
	v_mfma_scale_f32_32x32x64_f8f6f4 v[82:97], v[82:89], v[146:153], v[230:245], v194, v193 op_sel_hi:[0,0,0]
	v_exp_f32_e32 v0, v118
	v_exp_f32_e32 v177, v119
	v_exp_f32_e32 v179, v120
	v_exp_f32_e32 v254, v121
	v_add_f32_e32 v219, v0, v219
	v_add_f32_e32 v219, v177, v219
	v_cvt_pk_fp8_f32 v247, v0, v177
	v_add_f32_e32 v219, v179, v219
	v_add_f32_e32 v219, v254, v219
	v_cvt_pk_fp8_f32 v247, v179, v254 op_sel:[0,0,1]
	ds_read_b128 v[114:117], v213 offset:51200
	ds_read_b128 v[118:121], v214 offset:51200
	s_waitcnt lgkmcnt(2)
	v_mfma_scale_f32_32x32x64_f8f6f4 v[66:81], v[222:229], v[146:153], v[230:245], v194, v193 op_sel_hi:[0,0,0]
	ds_read_b128 v[222:225], v213 offset:55296
	ds_read_b128 v[226:229], v214 offset:55296
	v_exp_f32_e32 v0, v122
	v_exp_f32_e32 v177, v123
	v_exp_f32_e32 v179, v124
	v_exp_f32_e32 v254, v125
	v_add_f32_e32 v219, v0, v219
	v_add_f32_e32 v219, v177, v219
	v_cvt_pk_fp8_f32 v248, v0, v177
	v_add_f32_e32 v219, v179, v219
	v_add_f32_e32 v219, v254, v219
	v_cvt_pk_fp8_f32 v248, v179, v254 op_sel:[0,0,1]
	v_exp_f32_e32 v0, v126
	v_exp_f32_e32 v177, v127
	v_exp_f32_e32 v179, v128
	v_exp_f32_e32 v254, v129
	v_add_f32_e32 v219, v0, v219
	v_add_f32_e32 v219, v177, v219
	v_cvt_pk_fp8_f32 v249, v0, v177
	v_add_f32_e32 v219, v179, v219
	v_add_f32_e32 v219, v254, v219
	v_cvt_pk_fp8_f32 v249, v179, v254 op_sel:[0,0,1]
	ds_read_b128 v[122:125], v185 offset:59392
	ds_read_b128 v[126:129], v186 offset:59392
	s_waitcnt lgkmcnt(4)
	v_mfma_scale_f32_32x32x64_f8f6f4 v[82:97], v[114:121], v[138:145], v[82:97], v194, v193 op_sel_hi:[0,0,0]
	v_exp_f32_e32 v0, v98
	v_exp_f32_e32 v177, v99
	v_exp_f32_e32 v179, v100
	v_exp_f32_e32 v254, v101
	v_add_f32_e32 v219, v0, v219
	v_add_f32_e32 v219, v177, v219
	v_cvt_pk_fp8_f32 v250, v0, v177
	v_add_f32_e32 v219, v179, v219
	v_add_f32_e32 v219, v254, v219
	v_cvt_pk_fp8_f32 v250, v179, v254 op_sel:[0,0,1]
	s_waitcnt lgkmcnt(2)
	v_mfma_scale_f32_32x32x64_f8f6f4 v[66:81], v[222:229], v[138:145], v[66:81], v194, v193 op_sel_hi:[0,0,0]
	ds_read_b128 v[222:225], v185 offset:61440
	ds_read_b128 v[226:229], v186 offset:61440
	v_exp_f32_e32 v0, v102
	v_exp_f32_e32 v177, v103
	v_exp_f32_e32 v179, v104
	v_exp_f32_e32 v254, v105
	v_add_f32_e32 v219, v0, v219
	v_add_f32_e32 v219, v177, v219
	v_cvt_pk_fp8_f32 v251, v0, v177
	v_add_f32_e32 v219, v179, v219
	v_add_f32_e32 v219, v254, v219
	v_cvt_pk_fp8_f32 v251, v179, v254 op_sel:[0,0,1]
	v_exp_f32_e32 v0, v106
	v_exp_f32_e32 v177, v107
	v_exp_f32_e32 v179, v108
	v_exp_f32_e32 v254, v109
	v_add_f32_e32 v219, v0, v219
	v_add_f32_e32 v219, v177, v219
	v_cvt_pk_fp8_f32 v252, v0, v177
	v_add_f32_e32 v219, v179, v219
	v_add_f32_e32 v219, v254, v219
	v_cvt_pk_fp8_f32 v252, v179, v254 op_sel:[0,0,1]
	s_waitcnt lgkmcnt(2)
	v_mfma_scale_f32_32x32x64_f8f6f4 v[82:97], v[122:129], v[130:137], v[82:97], v194, v193 op_sel_hi:[0,0,0]
	v_exp_f32_e32 v0, v110
	v_exp_f32_e32 v177, v111
	v_exp_f32_e32 v179, v112
	v_exp_f32_e32 v254, v113
	v_add_f32_e32 v219, v0, v219
	v_add_f32_e32 v219, v177, v219
	v_cvt_pk_fp8_f32 v253, v0, v177
	v_add_f32_e32 v219, v179, v219
	v_add_f32_e32 v219, v254, v219
	v_cvt_pk_fp8_f32 v253, v179, v254 op_sel:[0,0,1]
	ds_read_b128 v[122:125], v185 offset:8192
	ds_read_b128 v[126:129], v186 offset:8192
	ds_read_b128 v[114:117], v185 offset:10240
	ds_read_b128 v[118:121], v186 offset:10240
	ds_read_b128 v[106:109], v185 offset:12288
	ds_read_b128 v[110:113], v186 offset:12288
	ds_read_b128 v[98:101], v185 offset:14336
	ds_read_b128 v[102:105], v186 offset:14336
	s_waitcnt lgkmcnt(8)
	v_mfma_scale_f32_32x32x64_f8f6f4 v[66:81], v[222:229], v[130:137], v[66:81], v194, v193 op_sel_hi:[0,0,0]
	v_mov_b32_e32 v0, v219
	s_nop 1
	v_permlane32_swap_b32_e32 v219, v0
	v_add_f32_e32 v219, v219, v0
	v_fma_f32 v209, v209, v221, v219
	v_max_f32_e32 v177, v82, v83
	v_max3_f32 v177, v177, v84, v85
	v_max3_f32 v177, v177, v86, v87
	v_max3_f32 v177, v177, v88, v89
	v_max3_f32 v177, v177, v90, v91
	v_max3_f32 v177, v177, v92, v93
	v_max3_f32 v177, v177, v94, v95
	v_max3_f32 v177, v177, v96, v97
	s_waitcnt lgkmcnt(6)
	v_mfma_scale_f32_32x32x64_f8f6f4 v[50:65], v[246:253], v[122:129], v[50:65], v194, v194 op_sel_hi:[0,0,0]
	s_waitcnt vmcnt(0)
	ds_write_b128 v210, v[158:161]
	ds_write_b128 v211, v[162:165] offset:16384
	s_waitcnt lgkmcnt(6)
	v_mfma_scale_f32_32x32x64_f8f6f4 v[34:49], v[246:253], v[114:121], v[34:49], v194, v194 op_sel_hi:[0,0,0]
	s_waitcnt lgkmcnt(0)
	s_barrier
	s_waitcnt lgkmcnt(2)
	v_mfma_scale_f32_32x32x64_f8f6f4 v[18:33], v[246:253], v[106:113], v[18:33], v194, v194 op_sel_hi:[0,0,0]
	s_waitcnt lgkmcnt(0)
	v_mfma_scale_f32_32x32x64_f8f6f4 v[2:17], v[246:253], v[98:105], v[2:17], v194, v194 op_sel_hi:[0,0,0]
	v_max_f32_e32 v0, v66, v67
	v_max3_f32 v0, v0, v68, v69
	v_max3_f32 v0, v0, v70, v71
	v_max3_f32 v0, v0, v72, v73
	v_max3_f32 v0, v0, v74, v75
	v_max3_f32 v0, v0, v76, v77
	v_max3_f32 v0, v0, v78, v79
	v_max3_f32 v0, v0, v80, v81
	v_max_f32_e32 v177, v177, v0
	v_mov_b32_e32 v0, v177
	v_mov_b32_e32 v218, 1.0
	s_nop 0
	v_permlane32_swap_b32_e32 v177, v0
	v_max_f32_e32 v177, v177, v0
	v_cmp_ge_f32_e32 vcc, s90, v177
	s_cmp_eq_u64 vcc, exec
	s_cbranch_scc0 .Lmla_q1_newmax
